# v42 + nt on read-once epilogue inputs (PE in EpiOut, r_conv in conv-merge, r_ssm in final merge), PE tile stores, carry Sloc loads
# baseline (speedup 1.0000x reference)
.LBB0_264:
	s_xor_b64 s[56:57], s[58:59], -1
	s_or_b32 s58, s27, s19
	s_ashr_i32 s59, s58, 31
	s_lshl_b64 s[30:31], s[58:59], 9
	s_add_u32 s60, s20, s30
	s_addc_u32 s61, s18, s31
	global_load_dwordx4 v[50:53], v2, s[60:61] nt
	v_lshl_add_u64 v[20:21], s[60:61], 0, v[2:3]
	s_movk_i32 s27, 0x2000
	s_movk_i32 s30, 0x6000
	v_mov_b32_e32 v22, 0
	s_waitcnt vmcnt(0)
	ds_write_b128 v23, v[50:53]
	v_add_co_u32_e32 v50, vcc, s27, v20
	s_mov_b32 s27, 0
	s_nop 0
	v_addc_co_u32_e32 v51, vcc, 0, v21, vcc
	global_load_dwordx4 v[50:53], v[50:51], off nt
	s_waitcnt vmcnt(0)
	ds_write_b128 v23, v[50:53] offset:8192
	global_load_dwordx4 v[50:53], v37, s[60:61] nt
	s_waitcnt vmcnt(0)
	ds_write_b128 v23, v[50:53] offset:16384
	v_add_co_u32_e32 v50, vcc, s30, v20
	s_mov_b32 s30, 0xa000
	s_nop 0
	v_addc_co_u32_e32 v51, vcc, 0, v21, vcc
	global_load_dwordx4 v[50:53], v[50:51], off nt
	s_waitcnt vmcnt(0)
	ds_write_b128 v23, v[50:53] offset:24576
	global_load_dwordx4 v[50:53], v38, s[60:61] nt
	s_waitcnt vmcnt(0)
	ds_write_b128 v23, v[50:53] offset:32768
	v_add_co_u32_e32 v50, vcc, s30, v20
	s_mov_b32 s30, 0xe000
	s_nop 0
	v_addc_co_u32_e32 v51, vcc, 0, v21, vcc
	global_load_dwordx4 v[50:53], v[50:51], off nt
	s_waitcnt vmcnt(0)
	ds_write_b128 v23, v[50:53] offset:40960
	global_load_dwordx4 v[50:53], v39, s[60:61] nt
	s_waitcnt vmcnt(0)
	ds_write_b128 v23, v[50:53] offset:49152
	v_add_co_u32_e32 v50, vcc, s30, v20
	s_mov_b32 s30, 0x12000
	s_nop 0
	v_addc_co_u32_e32 v51, vcc, 0, v21, vcc
	global_load_dwordx4 v[50:53], v[50:51], off nt
	s_waitcnt vmcnt(0)
	ds_write_b128 v23, v[50:53] offset:57344
	global_load_dwordx4 v[50:53], v40, s[60:61] nt
	s_waitcnt vmcnt(0)
	ds_write_b128 v25, v[50:53]
	v_add_co_u32_e32 v50, vcc, s30, v20
	s_mov_b32 s30, 0x16000
	s_nop 0
	v_addc_co_u32_e32 v51, vcc, 0, v21, vcc
	global_load_dwordx4 v[50:53], v[50:51], off nt
	s_waitcnt vmcnt(0)
	ds_write_b128 v26, v[50:53]
	global_load_dwordx4 v[50:53], v41, s[60:61] nt
	s_waitcnt vmcnt(0)
	ds_write_b128 v27, v[50:53]
	v_add_co_u32_e32 v50, vcc, s30, v20
	s_mov_b32 s30, 0x1a000
	s_nop 0
	v_addc_co_u32_e32 v51, vcc, 0, v21, vcc
	global_load_dwordx4 v[50:53], v[50:51], off nt
	s_waitcnt vmcnt(0)
	ds_write_b128 v28, v[50:53]
	global_load_dwordx4 v[50:53], v42, s[60:61] nt
	s_waitcnt vmcnt(0)
	ds_write_b128 v29, v[50:53]
	v_add_co_u32_e32 v50, vcc, s30, v20
	s_nop 1
	v_addc_co_u32_e32 v51, vcc, 0, v21, vcc
	global_load_dwordx4 v[50:53], v[50:51], off nt
	v_add_co_u32_e32 v20, vcc, 0x1e000, v20
	s_waitcnt vmcnt(0)
	ds_write_b128 v30, v[50:53]
	global_load_dwordx4 v[50:53], v43, s[60:61] nt
	v_addc_co_u32_e32 v21, vcc, 0, v21, vcc
	s_waitcnt vmcnt(0)
	ds_write_b128 v31, v[50:53]
	global_load_dwordx4 v[50:53], v[20:21], off nt
	v_mov_b32_e32 v20, 0
	s_waitcnt vmcnt(0)
	ds_write_b128 v32, v[50:53]
	s_waitcnt lgkmcnt(0)
	s_barrier

.LBB0_453:
	v_lshl_add_u32 v150, s91, 8, v144
	v_lshl_or_b32 v152, s92, 8, v146
	v_ashrrev_i32_e32 v151, 31, v150
	v_ashrrev_i32_e32 v153, 31, v152
	v_cvt_pk_bf16_f32 v126, v126, v127
	v_cvt_pk_bf16_f32 v127, v128, v129
	v_cvt_pk_bf16_f32 v128, v122, v123
	v_lshlrev_b64 v[122:123], 11, v[150:151]
	v_cvt_pk_bf16_f32 v129, v124, v125
	v_lshl_add_u64 v[122:123], s[6:7], 0, v[122:123]
	v_lshlrev_b64 v[124:125], 1, v[152:153]
	v_lshl_add_u64 v[122:123], v[122:123], 0, v[124:125]
	v_cvt_pk_bf16_f32 v110, v110, v111
	v_cvt_pk_bf16_f32 v111, v112, v113
	v_cvt_pk_bf16_f32 v112, v106, v107
	v_cvt_pk_bf16_f32 v113, v108, v109
	global_store_dwordx4 v[122:123], v[110:113], off offset:256 nt
	v_cvt_pk_bf16_f32 v94, v94, v95
	v_cvt_pk_bf16_f32 v95, v96, v97
	v_or_b32_e32 v110, 16, v150
	v_ashrrev_i32_e32 v111, 31, v110
	v_lshlrev_b64 v[110:111], 11, v[110:111]
	v_lshl_add_u64 v[110:111], s[6:7], 0, v[110:111]
	v_lshl_add_u64 v[110:111], v[110:111], 0, v[124:125]
	v_cvt_pk_bf16_f32 v96, v90, v91
	v_cvt_pk_bf16_f32 v97, v92, v93
	s_mov_b64 s[10:11], 0x40000
	global_store_dwordx4 v[110:111], v[94:97], off offset:256 nt
	v_cvt_pk_bf16_f32 v62, v62, v63
	v_cvt_pk_bf16_f32 v63, v64, v65
	v_or_b32_e32 v94, 32, v150
	v_cvt_pk_bf16_f32 v64, v58, v59
	v_lshl_add_u64 v[58:59], v[122:123], 0, s[10:11]
	s_mov_b32 s10, 0x40000
	v_ashrrev_i32_e32 v95, 31, v94
	v_cvt_pk_bf16_f32 v65, v60, v61
	v_add_co_u32_e32 v60, vcc, s10, v122
	v_cvt_pk_bf16_f32 v46, v46, v47
	v_cvt_pk_bf16_f32 v47, v48, v49
	v_cvt_pk_bf16_f32 v48, v42, v43
	v_cvt_pk_bf16_f32 v49, v44, v45
	s_mov_b64 s[10:11], 0x48000
	v_lshlrev_b64 v[94:95], 11, v[94:95]
	v_addc_co_u32_e32 v61, vcc, 0, v123, vcc
	global_store_dwordx4 v[58:59], v[46:49], off offset:256 nt
	v_lshl_add_u64 v[94:95], s[6:7], 0, v[94:95]
	v_cvt_pk_bf16_f32 v30, v30, v31
	v_lshl_add_u64 v[46:47], v[122:123], 0, s[10:11]
	s_mov_b32 s10, 0x48000
	v_add_co_u32_e32 v48, vcc, s10, v122
	v_cvt_pk_bf16_f32 v31, v32, v33
	v_cvt_pk_bf16_f32 v32, v26, v27
	v_cvt_pk_bf16_f32 v33, v28, v29
	s_mov_b64 s[10:11], 0x50000
	v_lshl_add_u64 v[94:95], v[94:95], 0, v[124:125]
	v_cvt_pk_bf16_f32 v78, v78, v79
	v_cvt_pk_bf16_f32 v79, v80, v81
	v_cvt_pk_bf16_f32 v80, v74, v75
	v_cvt_pk_bf16_f32 v81, v76, v77
	v_addc_co_u32_e32 v49, vcc, 0, v123, vcc
	global_store_dwordx4 v[46:47], v[30:33], off offset:256 nt
	global_store_dwordx4 v[94:95], v[78:81], off offset:256 nt
	v_cvt_pk_bf16_f32 v14, v14, v15
	v_lshl_add_u64 v[30:31], v[122:123], 0, s[10:11]
	s_mov_b32 s10, 0x50000
	v_or_b32_e32 v78, 48, v150
	v_add_co_u32_e32 v32, vcc, s10, v122
	v_cvt_pk_bf16_f32 v15, v16, v17
	v_cvt_pk_bf16_f32 v16, v10, v11
	v_cvt_pk_bf16_f32 v17, v12, v13
	s_mov_b64 s[10:11], 0x58000
	v_ashrrev_i32_e32 v79, 31, v78
	v_addc_co_u32_e32 v33, vcc, 0, v123, vcc
	global_store_dwordx4 v[30:31], v[14:17], off offset:256 nt
	v_lshlrev_b64 v[78:79], 11, v[78:79]
	v_lshl_add_u64 v[78:79], s[6:7], 0, v[78:79]
	v_lshl_add_u64 v[14:15], v[122:123], 0, s[10:11]
	s_mov_b32 s10, 0x58000
	v_add_co_u32_e32 v16, vcc, s10, v122
	v_cvt_pk_bf16_f32 v106, v118, v119
	s_nop 0
	v_addc_co_u32_e32 v17, vcc, 0, v123, vcc
	v_cvt_pk_bf16_f32 v107, v120, v121
	v_cvt_pk_bf16_f32 v108, v114, v115
	v_cvt_pk_bf16_f32 v109, v116, v117
	v_cvt_pk_bf16_f32 v90, v102, v103
	v_cvt_pk_bf16_f32 v91, v104, v105
	v_cvt_pk_bf16_f32 v92, v98, v99
	v_cvt_pk_bf16_f32 v93, v100, v101
	v_cvt_pk_bf16_f32 v74, v86, v87
	v_cvt_pk_bf16_f32 v75, v88, v89
	v_cvt_pk_bf16_f32 v76, v82, v83
	v_cvt_pk_bf16_f32 v77, v84, v85
	v_lshl_add_u64 v[78:79], v[78:79], 0, v[124:125]
	v_cvt_pk_bf16_f32 v70, v70, v71
	v_cvt_pk_bf16_f32 v71, v72, v73
	v_cvt_pk_bf16_f32 v72, v66, v67
	v_cvt_pk_bf16_f32 v73, v68, v69
	v_cvt_pk_bf16_f32 v42, v54, v55
	v_cvt_pk_bf16_f32 v43, v56, v57
	v_cvt_pk_bf16_f32 v44, v50, v51
	v_cvt_pk_bf16_f32 v45, v52, v53
	v_cvt_pk_bf16_f32 v26, v38, v39
	v_cvt_pk_bf16_f32 v27, v40, v41
	v_cvt_pk_bf16_f32 v28, v34, v35
	v_cvt_pk_bf16_f32 v29, v36, v37
	v_cvt_pk_bf16_f32 v10, v22, v23
	v_cvt_pk_bf16_f32 v11, v24, v25
	v_cvt_pk_bf16_f32 v12, v18, v19
	v_cvt_pk_bf16_f32 v13, v20, v21
	v_cvt_pk_bf16_f32 v6, v6, v7
	v_cvt_pk_bf16_f32 v7, v8, v9
	v_cvt_pk_bf16_f32 v8, v2, v3
	v_cvt_pk_bf16_f32 v9, v4, v5
	s_andn2_b64 vcc, exec, s[0:1]
	s_mov_b64 s[0:1], -1
	v_readlane_b32 s96, v254, 37
	global_store_dwordx4 v[122:123], v[126:129], off nt
	global_store_dwordx4 v[110:111], v[106:109], off nt
	global_store_dwordx4 v[94:95], v[90:93], off nt
	global_store_dwordx4 v[78:79], v[74:77], off nt
	global_store_dwordx4 v[78:79], v[70:73], off offset:256 nt
	global_store_dwordx4 v[60:61], v[62:65], off nt
	global_store_dwordx4 v[48:49], v[42:45], off nt
	global_store_dwordx4 v[32:33], v[26:29], off nt
	global_store_dwordx4 v[16:17], v[10:13], off nt
	global_store_dwordx4 v[14:15], v[6:9], off offset:256 nt
	s_cbranch_vccnz .LBB0_442
	s_andn2_b64 vcc, exec, s[4:5]
	s_cbranch_vccnz .LBB0_441
	s_barrier
	s_branch .LBB0_441

.LBB0_624:
	s_and_b32 s2, 0xffff, s22
	v_lshl_add_u32 v144, s83, 8, v132
	s_lshl_b32 s2, s2, 8
	v_add_u32_e32 v146, 0xb0, v144
	v_mov_b32_e32 v147, 0
	s_or_b32 s2, s2, s27
	v_lshlrev_b64 v[128:129], 10, v[146:147]
	v_or_b32_e32 v146, s2, v236
	v_lshl_add_u64 v[128:129], v[128:129], 0, v[146:147]
	v_lshlrev_b64 v[128:129], 1, v[128:129]
	v_or_b32_e32 v130, 0x100, v128
	v_mov_b32_e32 v131, v129
	v_lshl_add_u64 v[132:133], s[6:7], 0, v[130:131]
	v_lshl_add_u64 v[130:131], s[70:71], 0, v[130:131]
	global_load_dwordx4 v[136:139], v[132:133], off
	global_load_dwordx4 v[140:143], v[130:131], off nt
	v_lshl_add_u64 v[130:131], s[6:7], 0, v[128:129]
	v_lshl_add_u64 v[132:133], s[70:71], 0, v[128:129]
	global_load_dwordx4 v[128:131], v[130:131], off
	s_nop 0
	global_load_dwordx4 v[132:135], v[132:133], off nt
	s_waitcnt vmcnt(0)
	v_lshlrev_b32_e32 v145, 16, v138
	v_lshlrev_b32_e32 v148, 16, v142
	v_and_b32_e32 v142, 0xffff0000, v142
	v_and_b32_e32 v138, 0xffff0000, v138
	v_lshlrev_b32_e32 v149, 16, v139
	v_and_b32_e32 v139, 0xffff0000, v139
	v_mul_f32_e32 v145, 0xbfb8aa3b, v145
	v_mul_f32_e32 v148, 0xbfb8aa3b, v148
	v_mul_f32_e32 v142, 0xbfb8aa3b, v142
	v_lshlrev_b32_e32 v150, 16, v143
	v_and_b32_e32 v143, 0xffff0000, v143
	v_mul_f32_e32 v138, 0xbfb8aa3b, v138
	v_mul_f32_e32 v139, 0xbfb8aa3b, v139
	v_exp_f32_e32 v145, v145
	v_exp_f32_e32 v148, v148
	v_exp_f32_e32 v142, v142
	v_lshlrev_b32_e32 v153, 16, v137
	v_lshlrev_b32_e32 v154, 16, v141
	v_and_b32_e32 v137, 0xffff0000, v137
	v_and_b32_e32 v141, 0xffff0000, v141
	v_mul_f32_e32 v150, 0xbfb8aa3b, v150
	v_mul_f32_e32 v143, 0xbfb8aa3b, v143
	v_exp_f32_e32 v138, v138
	v_exp_f32_e32 v139, v139
	v_lshlrev_b32_e32 v151, 16, v136
	v_and_b32_e32 v136, 0xffff0000, v136
	v_mul_f32_e32 v154, 0xbfb8aa3b, v154
	v_mul_f32_e32 v137, 0xbfb8aa3b, v137
	v_mul_f32_e32 v141, 0xbfb8aa3b, v141
	v_exp_f32_e32 v150, v150
	v_exp_f32_e32 v143, v143
	v_mul_f32_e32 v136, 0xbfb8aa3b, v136
	v_exp_f32_e32 v154, v154
	v_exp_f32_e32 v156, v137
	v_exp_f32_e32 v137, v141
	v_lshlrev_b32_e32 v152, 16, v140
	v_and_b32_e32 v140, 0xffff0000, v140
	v_mul_f32_e32 v149, 0xbfb8aa3b, v149
	v_exp_f32_e32 v136, v136
	v_add_f32_e32 v141, 1.0, v145
	v_add_f32_e32 v145, 1.0, v148
	v_add_f32_e32 v142, 1.0, v142
	v_mul_f32_e32 v152, 0xbfb8aa3b, v152
	v_mul_f32_e32 v140, 0xbfb8aa3b, v140
	v_mul_f32_e32 v153, 0xbfb8aa3b, v153
	v_exp_f32_e32 v149, v149
	v_add_f32_e32 v148, 1.0, v138
	v_add_f32_e32 v155, 1.0, v139
	v_rcp_f32_e32 v138, v145
	v_rcp_f32_e32 v139, v142
	v_exp_f32_e32 v152, v152
	v_exp_f32_e32 v140, v140
	v_exp_f32_e32 v153, v153
	v_add_f32_e32 v150, 1.0, v150
	v_add_f32_e32 v143, 1.0, v143
	v_add_f32_e32 v154, 1.0, v154
	v_add_f32_e32 v159, 1.0, v137
	v_rcp_f32_e32 v142, v150
	v_rcp_f32_e32 v143, v143
	v_mul_f32_e32 v151, 0xbfb8aa3b, v151
	v_add_f32_e32 v157, 1.0, v136
	v_min_f32_e32 v136, 0x7149f2ca, v141
	v_min_f32_e32 v137, 0x7149f2ca, v148
	v_min_f32_e32 v141, 0x7149f2ca, v155
	v_rcp_f32_e32 v154, v154
	v_rcp_f32_e32 v155, v159
	v_exp_f32_e32 v151, v151
	v_add_f32_e32 v149, 1.0, v149
	v_pk_mul_f32 v[136:137], v[136:137], v[138:139]
	v_add_f32_e32 v152, 1.0, v152
	v_add_f32_e32 v158, 1.0, v140
	v_add_f32_e32 v153, 1.0, v153
	v_min_f32_e32 v140, 0x7149f2ca, v149
	v_pk_mul_f32 v[0:1], v[0:1], v[136:137]
	v_add_f32_e32 v136, 1.0, v156
	v_rcp_f32_e32 v150, v152
	v_min_f32_e32 v152, 0x7149f2ca, v153
	v_pk_mul_f32 v[138:139], v[140:141], v[142:143]
	v_min_f32_e32 v153, 0x7149f2ca, v136
	v_pk_mul_f32 v[2:3], v[2:3], v[138:139]
	v_pk_mul_f32 v[138:139], v[152:153], v[154:155]
	v_add_f32_e32 v151, 1.0, v151
	v_pk_mul_f32 v[6:7], v[6:7], v[138:139]
	v_lshlrev_b32_e32 v138, 16, v130
	v_min_f32_e32 v148, 0x7149f2ca, v151
	v_rcp_f32_e32 v151, v158
	v_mul_f32_e32 v138, 0xbfb8aa3b, v138
	v_exp_f32_e32 v138, v138
	v_min_f32_e32 v149, 0x7149f2ca, v157
	v_pk_mul_f32 v[136:137], v[148:149], v[150:151]
	v_lshlrev_b32_e32 v139, 16, v134
	v_pk_mul_f32 v[4:5], v[4:5], v[136:137]
	v_add_f32_e32 v136, 1.0, v138
	v_min_f32_e32 v148, 0x7149f2ca, v136
	v_add_u32_e32 v136, 0xa0, v144
	v_mov_b32_e32 v137, v147
	v_mul_f32_e32 v139, 0xbfb8aa3b, v139
	v_lshlrev_b64 v[136:137], 10, v[136:137]
	v_exp_f32_e32 v139, v139
	v_lshl_add_u64 v[136:137], v[136:137], 0, v[146:147]
	v_lshlrev_b64 v[150:151], 1, v[136:137]
	v_or_b32_e32 v140, 0x100, v150
	v_mov_b32_e32 v141, v151
	v_lshl_add_u64 v[136:137], s[6:7], 0, v[140:141]
	v_add_f32_e32 v145, 1.0, v139
	global_load_dwordx4 v[136:139], v[136:137], off
	v_lshl_add_u64 v[140:141], s[70:71], 0, v[140:141]
	global_load_dwordx4 v[140:143], v[140:141], off nt
	v_and_b32_e32 v130, 0xffff0000, v130
	v_mul_f32_e32 v130, 0xbfb8aa3b, v130
	v_and_b32_e32 v134, 0xffff0000, v134
	v_exp_f32_e32 v130, v130
	v_mul_f32_e32 v134, 0xbfb8aa3b, v134
	v_exp_f32_e32 v134, v134
	v_rcp_f32_e32 v152, v145
	v_add_f32_e32 v130, 1.0, v130
	v_min_f32_e32 v149, 0x7149f2ca, v130
	v_add_f32_e32 v130, 1.0, v134
	v_lshlrev_b32_e32 v134, 16, v131
	v_lshlrev_b32_e32 v145, 16, v135
	v_and_b32_e32 v135, 0xffff0000, v135
	v_mul_f32_e32 v134, 0xbfb8aa3b, v134
	v_mul_f32_e32 v145, 0xbfb8aa3b, v145
	v_mul_f32_e32 v135, 0xbfb8aa3b, v135
	v_exp_f32_e32 v134, v134
	v_exp_f32_e32 v145, v145
	v_exp_f32_e32 v135, v135
	v_and_b32_e32 v131, 0xffff0000, v131
	v_mul_f32_e32 v131, 0xbfb8aa3b, v131
	v_exp_f32_e32 v131, v131
	v_rcp_f32_e32 v153, v130
	v_add_f32_e32 v130, 1.0, v134
	v_add_f32_e32 v134, 1.0, v145
	v_add_f32_e32 v135, 1.0, v135
	v_rcp_f32_e32 v134, v134
	v_rcp_f32_e32 v135, v135
	v_add_f32_e32 v131, 1.0, v131
	v_min_f32_e32 v130, 0x7149f2ca, v130
	v_min_f32_e32 v131, 0x7149f2ca, v131
	v_pk_mul_f32 v[130:131], v[130:131], v[134:135]
	v_lshlrev_b32_e32 v135, 16, v133
	v_pk_mul_f32 v[10:11], v[10:11], v[130:131]
	v_lshlrev_b32_e32 v130, 16, v128
	v_lshlrev_b32_e32 v131, 16, v132
	v_and_b32_e32 v128, 0xffff0000, v128
	v_mul_f32_e32 v131, 0xbfb8aa3b, v131
	v_mul_f32_e32 v128, 0xbfb8aa3b, v128
	v_and_b32_e32 v132, 0xffff0000, v132
	v_exp_f32_e32 v131, v131
	v_exp_f32_e32 v128, v128
	v_mul_f32_e32 v132, 0xbfb8aa3b, v132
	v_exp_f32_e32 v132, v132
	v_add_f32_e32 v131, 1.0, v131
	v_add_f32_e32 v128, 1.0, v128
	v_rcp_f32_e32 v134, v131
	v_min_f32_e32 v131, 0x7149f2ca, v128
	v_add_f32_e32 v128, 1.0, v132
	v_lshlrev_b32_e32 v132, 16, v129
	v_and_b32_e32 v133, 0xffff0000, v133
	v_mul_f32_e32 v132, 0xbfb8aa3b, v132
	v_mul_f32_e32 v135, 0xbfb8aa3b, v135
	v_mul_f32_e32 v133, 0xbfb8aa3b, v133
	v_exp_f32_e32 v132, v132
	v_exp_f32_e32 v145, v135
	v_exp_f32_e32 v133, v133
	v_and_b32_e32 v129, 0xffff0000, v129
	v_mul_f32_e32 v129, 0xbfb8aa3b, v129
	v_exp_f32_e32 v129, v129
	v_rcp_f32_e32 v135, v128
	v_add_f32_e32 v128, 1.0, v132
	v_add_f32_e32 v132, 1.0, v145
	v_add_f32_e32 v133, 1.0, v133
	v_rcp_f32_e32 v132, v132
	v_rcp_f32_e32 v133, v133
	v_add_f32_e32 v129, 1.0, v129
	v_min_f32_e32 v128, 0x7149f2ca, v128
	v_min_f32_e32 v129, 0x7149f2ca, v129
	v_pk_mul_f32 v[128:129], v[128:129], v[132:133]
	v_mul_f32_e32 v130, 0xbfb8aa3b, v130
	v_pk_mul_f32 v[14:15], v[14:15], v[128:129]
	v_exp_f32_e32 v130, v130
	v_pk_mul_f32 v[148:149], v[148:149], v[152:153]
	v_add_f32_e32 v130, 1.0, v130
	s_waitcnt vmcnt(1)
	v_lshlrev_b32_e32 v128, 16, v138
	v_mul_f32_e32 v128, 0xbfb8aa3b, v128
	s_waitcnt vmcnt(0)
	v_lshlrev_b32_e32 v129, 16, v142
	v_exp_f32_e32 v128, v128
	v_mul_f32_e32 v129, 0xbfb8aa3b, v129
	v_exp_f32_e32 v129, v129
	v_min_f32_e32 v130, 0x7149f2ca, v130
	v_add_f32_e32 v128, 1.0, v128
	v_pk_mul_f32 v[8:9], v[8:9], v[148:149]
	v_pk_mul_f32 v[130:131], v[130:131], v[134:135]
	v_min_f32_e32 v148, 0x7149f2ca, v128
	v_add_f32_e32 v145, 1.0, v129
	v_and_b32_e32 v132, 0xffff0000, v138
	v_lshl_add_u64 v[128:129], s[6:7], 0, v[150:151]
	v_pk_mul_f32 v[12:13], v[12:13], v[130:131]
	global_load_dwordx4 v[128:131], v[128:129], off
	v_mul_f32_e32 v138, 0xbfb8aa3b, v132
	v_lshl_add_u64 v[132:133], s[70:71], 0, v[150:151]
	global_load_dwordx4 v[132:135], v[132:133], off nt
	v_and_b32_e32 v142, 0xffff0000, v142
	v_exp_f32_e32 v138, v138
	v_mul_f32_e32 v142, 0xbfb8aa3b, v142
	v_exp_f32_e32 v142, v142
	v_rcp_f32_e32 v150, v145
	v_add_f32_e32 v138, 1.0, v138
	v_min_f32_e32 v149, 0x7149f2ca, v138
	v_add_f32_e32 v138, 1.0, v142
	v_lshlrev_b32_e32 v142, 16, v139
	v_lshlrev_b32_e32 v145, 16, v143
	v_and_b32_e32 v143, 0xffff0000, v143
	v_mul_f32_e32 v142, 0xbfb8aa3b, v142
	v_mul_f32_e32 v145, 0xbfb8aa3b, v145
	v_mul_f32_e32 v143, 0xbfb8aa3b, v143
	v_exp_f32_e32 v142, v142
	v_exp_f32_e32 v145, v145
	v_exp_f32_e32 v143, v143
	v_and_b32_e32 v139, 0xffff0000, v139
	v_mul_f32_e32 v139, 0xbfb8aa3b, v139
	v_exp_f32_e32 v139, v139
	v_rcp_f32_e32 v151, v138
	v_add_f32_e32 v138, 1.0, v142
	v_add_f32_e32 v142, 1.0, v145
	v_add_f32_e32 v143, 1.0, v143
	v_rcp_f32_e32 v142, v142
	v_rcp_f32_e32 v143, v143
	v_add_f32_e32 v139, 1.0, v139
	v_min_f32_e32 v138, 0x7149f2ca, v138
	v_min_f32_e32 v139, 0x7149f2ca, v139
	v_pk_mul_f32 v[138:139], v[138:139], v[142:143]
	v_lshlrev_b32_e32 v143, 16, v141
	v_pk_mul_f32 v[18:19], v[18:19], v[138:139]
	v_lshlrev_b32_e32 v138, 16, v136
	v_lshlrev_b32_e32 v139, 16, v140
	v_and_b32_e32 v136, 0xffff0000, v136
	v_mul_f32_e32 v139, 0xbfb8aa3b, v139
	v_mul_f32_e32 v136, 0xbfb8aa3b, v136
	v_and_b32_e32 v140, 0xffff0000, v140
	v_exp_f32_e32 v139, v139
	v_exp_f32_e32 v136, v136
	v_mul_f32_e32 v140, 0xbfb8aa3b, v140
	v_exp_f32_e32 v140, v140
	v_add_f32_e32 v139, 1.0, v139
	v_add_f32_e32 v136, 1.0, v136
	v_rcp_f32_e32 v142, v139
	v_min_f32_e32 v139, 0x7149f2ca, v136
	v_add_f32_e32 v136, 1.0, v140
	v_lshlrev_b32_e32 v140, 16, v137
	v_and_b32_e32 v141, 0xffff0000, v141
	v_mul_f32_e32 v140, 0xbfb8aa3b, v140
	v_mul_f32_e32 v143, 0xbfb8aa3b, v143
	v_mul_f32_e32 v141, 0xbfb8aa3b, v141
	v_exp_f32_e32 v140, v140
	v_exp_f32_e32 v145, v143
	v_exp_f32_e32 v141, v141
	v_and_b32_e32 v137, 0xffff0000, v137
	v_mul_f32_e32 v137, 0xbfb8aa3b, v137
	v_exp_f32_e32 v137, v137
	v_rcp_f32_e32 v143, v136
	v_add_f32_e32 v136, 1.0, v140
	v_add_f32_e32 v140, 1.0, v145
	v_add_f32_e32 v141, 1.0, v141
	v_rcp_f32_e32 v140, v140
	v_rcp_f32_e32 v141, v141
	v_add_f32_e32 v137, 1.0, v137
	v_min_f32_e32 v136, 0x7149f2ca, v136
	v_min_f32_e32 v137, 0x7149f2ca, v137
	v_pk_mul_f32 v[136:137], v[136:137], v[140:141]
	v_mul_f32_e32 v138, 0xbfb8aa3b, v138
	v_pk_mul_f32 v[22:23], v[22:23], v[136:137]
	v_pk_mul_f32 v[148:149], v[148:149], v[150:151]
	v_exp_f32_e32 v138, v138
	v_pk_mul_f32 v[16:17], v[16:17], v[148:149]
	v_add_f32_e32 v138, 1.0, v138
	s_waitcnt vmcnt(1)
	v_lshlrev_b32_e32 v136, 16, v130
	v_mul_f32_e32 v136, 0xbfb8aa3b, v136
	v_exp_f32_e32 v136, v136
	s_waitcnt vmcnt(0)
	v_lshlrev_b32_e32 v137, 16, v134
	v_mul_f32_e32 v137, 0xbfb8aa3b, v137
	v_exp_f32_e32 v137, v137
	v_add_f32_e32 v136, 1.0, v136
	v_min_f32_e32 v148, 0x7149f2ca, v136
	v_add_u32_e32 v136, 0x90, v144
	v_add_f32_e32 v145, 1.0, v137
	v_mov_b32_e32 v137, v147
	v_lshlrev_b64 v[136:137], 10, v[136:137]
	v_lshl_add_u64 v[136:137], v[136:137], 0, v[146:147]
	v_lshlrev_b64 v[150:151], 1, v[136:137]
	v_min_f32_e32 v138, 0x7149f2ca, v138
	v_or_b32_e32 v140, 0x100, v150
	v_mov_b32_e32 v141, v151
	v_pk_mul_f32 v[138:139], v[138:139], v[142:143]
	v_lshl_add_u64 v[136:137], s[6:7], 0, v[140:141]
	v_pk_mul_f32 v[20:21], v[20:21], v[138:139]
	global_load_dwordx4 v[136:139], v[136:137], off
	v_lshl_add_u64 v[140:141], s[70:71], 0, v[140:141]
	global_load_dwordx4 v[140:143], v[140:141], off nt
	v_and_b32_e32 v130, 0xffff0000, v130
	v_mul_f32_e32 v130, 0xbfb8aa3b, v130
	v_and_b32_e32 v134, 0xffff0000, v134
	v_exp_f32_e32 v130, v130
	v_mul_f32_e32 v134, 0xbfb8aa3b, v134
	v_exp_f32_e32 v134, v134
	v_rcp_f32_e32 v152, v145
	v_add_f32_e32 v130, 1.0, v130
	v_min_f32_e32 v149, 0x7149f2ca, v130
	v_add_f32_e32 v130, 1.0, v134
	v_lshlrev_b32_e32 v134, 16, v131
	v_lshlrev_b32_e32 v145, 16, v135
	v_and_b32_e32 v135, 0xffff0000, v135
	v_mul_f32_e32 v134, 0xbfb8aa3b, v134
	v_mul_f32_e32 v145, 0xbfb8aa3b, v145
	v_mul_f32_e32 v135, 0xbfb8aa3b, v135
	v_exp_f32_e32 v134, v134
	v_exp_f32_e32 v145, v145
	v_exp_f32_e32 v135, v135
	v_and_b32_e32 v131, 0xffff0000, v131
	v_mul_f32_e32 v131, 0xbfb8aa3b, v131
	v_exp_f32_e32 v131, v131
	v_rcp_f32_e32 v153, v130
	v_add_f32_e32 v130, 1.0, v134
	v_add_f32_e32 v134, 1.0, v145
	v_add_f32_e32 v135, 1.0, v135
	v_rcp_f32_e32 v134, v134
	v_rcp_f32_e32 v135, v135
	v_add_f32_e32 v131, 1.0, v131
	v_min_f32_e32 v130, 0x7149f2ca, v130
	v_min_f32_e32 v131, 0x7149f2ca, v131
	v_pk_mul_f32 v[130:131], v[130:131], v[134:135]
	v_lshlrev_b32_e32 v135, 16, v133
	v_pk_mul_f32 v[26:27], v[26:27], v[130:131]
	v_lshlrev_b32_e32 v130, 16, v128
	v_lshlrev_b32_e32 v131, 16, v132
	v_and_b32_e32 v128, 0xffff0000, v128
	v_mul_f32_e32 v131, 0xbfb8aa3b, v131
	v_mul_f32_e32 v128, 0xbfb8aa3b, v128
	v_and_b32_e32 v132, 0xffff0000, v132
	v_exp_f32_e32 v131, v131
	v_exp_f32_e32 v128, v128
	v_mul_f32_e32 v132, 0xbfb8aa3b, v132
	v_exp_f32_e32 v132, v132
	v_add_f32_e32 v131, 1.0, v131
	v_add_f32_e32 v128, 1.0, v128
	v_rcp_f32_e32 v134, v131
	v_min_f32_e32 v131, 0x7149f2ca, v128
	v_add_f32_e32 v128, 1.0, v132
	v_lshlrev_b32_e32 v132, 16, v129
	v_and_b32_e32 v133, 0xffff0000, v133
	v_mul_f32_e32 v132, 0xbfb8aa3b, v132
	v_mul_f32_e32 v135, 0xbfb8aa3b, v135
	v_mul_f32_e32 v133, 0xbfb8aa3b, v133
	v_exp_f32_e32 v132, v132
	v_exp_f32_e32 v145, v135
	v_exp_f32_e32 v133, v133
	v_and_b32_e32 v129, 0xffff0000, v129
	v_mul_f32_e32 v129, 0xbfb8aa3b, v129
	v_exp_f32_e32 v129, v129
	v_rcp_f32_e32 v135, v128
	v_add_f32_e32 v128, 1.0, v132
	v_add_f32_e32 v132, 1.0, v145
	v_add_f32_e32 v133, 1.0, v133
	v_rcp_f32_e32 v132, v132
	v_rcp_f32_e32 v133, v133
	v_add_f32_e32 v129, 1.0, v129
	v_min_f32_e32 v128, 0x7149f2ca, v128
	v_min_f32_e32 v129, 0x7149f2ca, v129
	v_pk_mul_f32 v[128:129], v[128:129], v[132:133]
	v_mul_f32_e32 v130, 0xbfb8aa3b, v130
	v_pk_mul_f32 v[30:31], v[30:31], v[128:129]
	v_exp_f32_e32 v130, v130
	v_pk_mul_f32 v[148:149], v[148:149], v[152:153]
	v_add_f32_e32 v130, 1.0, v130
	s_waitcnt vmcnt(1)
	v_lshlrev_b32_e32 v128, 16, v138
	v_mul_f32_e32 v128, 0xbfb8aa3b, v128
	s_waitcnt vmcnt(0)
	v_lshlrev_b32_e32 v129, 16, v142
	v_exp_f32_e32 v128, v128
	v_mul_f32_e32 v129, 0xbfb8aa3b, v129
	v_exp_f32_e32 v129, v129
	v_min_f32_e32 v130, 0x7149f2ca, v130
	v_add_f32_e32 v128, 1.0, v128
	v_pk_mul_f32 v[24:25], v[24:25], v[148:149]
	v_pk_mul_f32 v[130:131], v[130:131], v[134:135]
	v_min_f32_e32 v148, 0x7149f2ca, v128
	v_add_f32_e32 v145, 1.0, v129
	v_and_b32_e32 v132, 0xffff0000, v138
	v_lshl_add_u64 v[128:129], s[6:7], 0, v[150:151]
	v_pk_mul_f32 v[28:29], v[28:29], v[130:131]
	global_load_dwordx4 v[128:131], v[128:129], off
	v_mul_f32_e32 v138, 0xbfb8aa3b, v132
	v_lshl_add_u64 v[132:133], s[70:71], 0, v[150:151]
	global_load_dwordx4 v[132:135], v[132:133], off nt
	v_and_b32_e32 v142, 0xffff0000, v142
	v_exp_f32_e32 v138, v138
	v_mul_f32_e32 v142, 0xbfb8aa3b, v142
	v_exp_f32_e32 v142, v142
	v_rcp_f32_e32 v150, v145
	v_add_f32_e32 v138, 1.0, v138
	v_min_f32_e32 v149, 0x7149f2ca, v138
	v_add_f32_e32 v138, 1.0, v142
	v_lshlrev_b32_e32 v142, 16, v139
	v_lshlrev_b32_e32 v145, 16, v143
	v_and_b32_e32 v143, 0xffff0000, v143
	v_mul_f32_e32 v142, 0xbfb8aa3b, v142
	v_mul_f32_e32 v145, 0xbfb8aa3b, v145
	v_mul_f32_e32 v143, 0xbfb8aa3b, v143
	v_exp_f32_e32 v142, v142
	v_exp_f32_e32 v145, v145
	v_exp_f32_e32 v143, v143
	v_and_b32_e32 v139, 0xffff0000, v139
	v_mul_f32_e32 v139, 0xbfb8aa3b, v139
	v_exp_f32_e32 v139, v139
	v_rcp_f32_e32 v151, v138
	v_add_f32_e32 v138, 1.0, v142
	v_add_f32_e32 v142, 1.0, v145
	v_add_f32_e32 v143, 1.0, v143
	v_rcp_f32_e32 v142, v142
	v_rcp_f32_e32 v143, v143
	v_add_f32_e32 v139, 1.0, v139
	v_min_f32_e32 v138, 0x7149f2ca, v138
	v_min_f32_e32 v139, 0x7149f2ca, v139
	v_pk_mul_f32 v[138:139], v[138:139], v[142:143]
	v_lshlrev_b32_e32 v143, 16, v141
	v_pk_mul_f32 v[34:35], v[34:35], v[138:139]
	v_lshlrev_b32_e32 v138, 16, v136
	v_lshlrev_b32_e32 v139, 16, v140
	v_and_b32_e32 v136, 0xffff0000, v136
	v_mul_f32_e32 v139, 0xbfb8aa3b, v139
	v_mul_f32_e32 v136, 0xbfb8aa3b, v136
	v_and_b32_e32 v140, 0xffff0000, v140
	v_exp_f32_e32 v139, v139
	v_exp_f32_e32 v136, v136
	v_mul_f32_e32 v140, 0xbfb8aa3b, v140
	v_exp_f32_e32 v140, v140
	v_add_f32_e32 v139, 1.0, v139
	v_add_f32_e32 v136, 1.0, v136
	v_rcp_f32_e32 v142, v139
	v_min_f32_e32 v139, 0x7149f2ca, v136
	v_add_f32_e32 v136, 1.0, v140
	v_lshlrev_b32_e32 v140, 16, v137
	v_and_b32_e32 v141, 0xffff0000, v141
	v_mul_f32_e32 v140, 0xbfb8aa3b, v140
	v_mul_f32_e32 v143, 0xbfb8aa3b, v143
	v_mul_f32_e32 v141, 0xbfb8aa3b, v141
	v_exp_f32_e32 v140, v140
	v_exp_f32_e32 v145, v143
	v_exp_f32_e32 v141, v141
	v_and_b32_e32 v137, 0xffff0000, v137
	v_mul_f32_e32 v137, 0xbfb8aa3b, v137
	v_exp_f32_e32 v137, v137
	v_rcp_f32_e32 v143, v136
	v_add_f32_e32 v136, 1.0, v140
	v_add_f32_e32 v140, 1.0, v145
	v_add_f32_e32 v141, 1.0, v141
	v_rcp_f32_e32 v140, v140
	v_rcp_f32_e32 v141, v141
	v_add_f32_e32 v137, 1.0, v137
	v_min_f32_e32 v136, 0x7149f2ca, v136
	v_min_f32_e32 v137, 0x7149f2ca, v137
	v_pk_mul_f32 v[136:137], v[136:137], v[140:141]
	v_mul_f32_e32 v138, 0xbfb8aa3b, v138
	v_pk_mul_f32 v[38:39], v[38:39], v[136:137]
	v_pk_mul_f32 v[148:149], v[148:149], v[150:151]
	v_exp_f32_e32 v138, v138
	v_pk_mul_f32 v[32:33], v[32:33], v[148:149]
	v_add_f32_e32 v138, 1.0, v138
	s_waitcnt vmcnt(1)
	v_lshlrev_b32_e32 v136, 16, v130
	v_mul_f32_e32 v136, 0xbfb8aa3b, v136
	v_exp_f32_e32 v136, v136
	s_waitcnt vmcnt(0)
	v_lshlrev_b32_e32 v137, 16, v134
	v_mul_f32_e32 v137, 0xbfb8aa3b, v137
	v_exp_f32_e32 v137, v137
	v_add_f32_e32 v136, 1.0, v136
	v_min_f32_e32 v148, 0x7149f2ca, v136
	v_add_u32_e32 v136, 0x80, v144
	v_add_f32_e32 v145, 1.0, v137
	v_mov_b32_e32 v137, v147
	v_lshlrev_b64 v[136:137], 10, v[136:137]
	v_lshl_add_u64 v[136:137], v[136:137], 0, v[146:147]
	v_lshlrev_b64 v[150:151], 1, v[136:137]
	v_min_f32_e32 v138, 0x7149f2ca, v138
	v_or_b32_e32 v140, 0x100, v150
	v_mov_b32_e32 v141, v151
	v_pk_mul_f32 v[138:139], v[138:139], v[142:143]
	v_lshl_add_u64 v[136:137], s[6:7], 0, v[140:141]
	v_pk_mul_f32 v[36:37], v[36:37], v[138:139]
	global_load_dwordx4 v[136:139], v[136:137], off
	v_lshl_add_u64 v[140:141], s[70:71], 0, v[140:141]
	global_load_dwordx4 v[140:143], v[140:141], off nt
	v_and_b32_e32 v130, 0xffff0000, v130
	v_mul_f32_e32 v130, 0xbfb8aa3b, v130
	v_and_b32_e32 v134, 0xffff0000, v134
	v_exp_f32_e32 v130, v130
	v_mul_f32_e32 v134, 0xbfb8aa3b, v134
	v_exp_f32_e32 v134, v134
	v_rcp_f32_e32 v152, v145
	v_add_f32_e32 v130, 1.0, v130
	v_min_f32_e32 v149, 0x7149f2ca, v130
	v_add_f32_e32 v130, 1.0, v134
	v_lshlrev_b32_e32 v134, 16, v131
	v_lshlrev_b32_e32 v145, 16, v135
	v_and_b32_e32 v135, 0xffff0000, v135
	v_mul_f32_e32 v134, 0xbfb8aa3b, v134
	v_mul_f32_e32 v145, 0xbfb8aa3b, v145
	v_mul_f32_e32 v135, 0xbfb8aa3b, v135
	v_exp_f32_e32 v134, v134
	v_exp_f32_e32 v145, v145
	v_exp_f32_e32 v135, v135
	v_and_b32_e32 v131, 0xffff0000, v131
	v_mul_f32_e32 v131, 0xbfb8aa3b, v131
	v_exp_f32_e32 v131, v131
	v_rcp_f32_e32 v153, v130
	v_add_f32_e32 v130, 1.0, v134
	v_add_f32_e32 v134, 1.0, v145
	v_add_f32_e32 v135, 1.0, v135
	v_rcp_f32_e32 v134, v134
	v_rcp_f32_e32 v135, v135
	v_add_f32_e32 v131, 1.0, v131
	v_min_f32_e32 v130, 0x7149f2ca, v130
	v_min_f32_e32 v131, 0x7149f2ca, v131
	v_pk_mul_f32 v[130:131], v[130:131], v[134:135]
	v_lshlrev_b32_e32 v135, 16, v133
	v_pk_mul_f32 v[54:55], v[54:55], v[130:131]
	v_lshlrev_b32_e32 v130, 16, v128
	v_lshlrev_b32_e32 v131, 16, v132
	v_and_b32_e32 v128, 0xffff0000, v128
	v_mul_f32_e32 v131, 0xbfb8aa3b, v131
	v_mul_f32_e32 v128, 0xbfb8aa3b, v128
	v_and_b32_e32 v132, 0xffff0000, v132
	v_exp_f32_e32 v131, v131
	v_exp_f32_e32 v128, v128
	v_mul_f32_e32 v132, 0xbfb8aa3b, v132
	v_exp_f32_e32 v132, v132
	v_add_f32_e32 v131, 1.0, v131
	v_add_f32_e32 v128, 1.0, v128
	v_rcp_f32_e32 v134, v131
	v_min_f32_e32 v131, 0x7149f2ca, v128
	v_add_f32_e32 v128, 1.0, v132
	v_lshlrev_b32_e32 v132, 16, v129
	v_and_b32_e32 v133, 0xffff0000, v133
	v_mul_f32_e32 v132, 0xbfb8aa3b, v132
	v_mul_f32_e32 v135, 0xbfb8aa3b, v135
	v_mul_f32_e32 v133, 0xbfb8aa3b, v133
	v_exp_f32_e32 v132, v132
	v_exp_f32_e32 v145, v135
	v_exp_f32_e32 v133, v133
	v_and_b32_e32 v129, 0xffff0000, v129
	v_mul_f32_e32 v129, 0xbfb8aa3b, v129
	v_exp_f32_e32 v129, v129
	v_rcp_f32_e32 v135, v128
	v_add_f32_e32 v128, 1.0, v132
	v_add_f32_e32 v132, 1.0, v145
	v_add_f32_e32 v133, 1.0, v133
	v_rcp_f32_e32 v132, v132
	v_rcp_f32_e32 v133, v133
	v_add_f32_e32 v129, 1.0, v129
	v_min_f32_e32 v128, 0x7149f2ca, v128
	v_min_f32_e32 v129, 0x7149f2ca, v129
	v_pk_mul_f32 v[128:129], v[128:129], v[132:133]
	v_mul_f32_e32 v130, 0xbfb8aa3b, v130
	v_pk_mul_f32 v[62:63], v[62:63], v[128:129]
	v_exp_f32_e32 v130, v130
	v_pk_mul_f32 v[148:149], v[148:149], v[152:153]
	v_add_f32_e32 v130, 1.0, v130
	s_waitcnt vmcnt(1)
	v_lshlrev_b32_e32 v128, 16, v138
	v_mul_f32_e32 v128, 0xbfb8aa3b, v128
	s_waitcnt vmcnt(0)
	v_lshlrev_b32_e32 v129, 16, v142
	v_exp_f32_e32 v128, v128
	v_mul_f32_e32 v129, 0xbfb8aa3b, v129
	v_exp_f32_e32 v129, v129
	v_min_f32_e32 v130, 0x7149f2ca, v130
	v_add_f32_e32 v128, 1.0, v128
	v_pk_mul_f32 v[52:53], v[52:53], v[148:149]
	v_pk_mul_f32 v[130:131], v[130:131], v[134:135]
	v_min_f32_e32 v148, 0x7149f2ca, v128
	v_add_f32_e32 v145, 1.0, v129
	v_and_b32_e32 v132, 0xffff0000, v138
	v_lshl_add_u64 v[128:129], s[6:7], 0, v[150:151]
	v_pk_mul_f32 v[60:61], v[60:61], v[130:131]
	global_load_dwordx4 v[128:131], v[128:129], off
	v_mul_f32_e32 v138, 0xbfb8aa3b, v132
	v_lshl_add_u64 v[132:133], s[70:71], 0, v[150:151]
	global_load_dwordx4 v[132:135], v[132:133], off nt
	v_and_b32_e32 v142, 0xffff0000, v142
	v_exp_f32_e32 v138, v138
	v_mul_f32_e32 v142, 0xbfb8aa3b, v142
	v_exp_f32_e32 v142, v142
	v_rcp_f32_e32 v150, v145
	v_add_f32_e32 v138, 1.0, v138
	v_min_f32_e32 v149, 0x7149f2ca, v138
	v_add_f32_e32 v138, 1.0, v142
	v_lshlrev_b32_e32 v142, 16, v139
	v_lshlrev_b32_e32 v145, 16, v143
	v_and_b32_e32 v143, 0xffff0000, v143
	v_mul_f32_e32 v142, 0xbfb8aa3b, v142
	v_mul_f32_e32 v145, 0xbfb8aa3b, v145
	v_mul_f32_e32 v143, 0xbfb8aa3b, v143
	v_exp_f32_e32 v142, v142
	v_exp_f32_e32 v145, v145
	v_exp_f32_e32 v143, v143
	v_and_b32_e32 v139, 0xffff0000, v139
	v_mul_f32_e32 v139, 0xbfb8aa3b, v139
	v_exp_f32_e32 v139, v139
	v_rcp_f32_e32 v151, v138
	v_add_f32_e32 v138, 1.0, v142
	v_add_f32_e32 v142, 1.0, v145
	v_add_f32_e32 v143, 1.0, v143
	v_rcp_f32_e32 v142, v142
	v_rcp_f32_e32 v143, v143
	v_add_f32_e32 v139, 1.0, v139
	v_min_f32_e32 v138, 0x7149f2ca, v138
	v_min_f32_e32 v139, 0x7149f2ca, v139
	v_pk_mul_f32 v[138:139], v[138:139], v[142:143]
	v_lshlrev_b32_e32 v143, 16, v141
	v_pk_mul_f32 v[74:75], v[74:75], v[138:139]
	v_lshlrev_b32_e32 v138, 16, v136
	v_lshlrev_b32_e32 v139, 16, v140
	v_and_b32_e32 v136, 0xffff0000, v136
	v_mul_f32_e32 v139, 0xbfb8aa3b, v139
	v_mul_f32_e32 v136, 0xbfb8aa3b, v136
	v_and_b32_e32 v140, 0xffff0000, v140
	v_exp_f32_e32 v139, v139
	v_exp_f32_e32 v136, v136
	v_mul_f32_e32 v140, 0xbfb8aa3b, v140
	v_exp_f32_e32 v140, v140
	v_add_f32_e32 v139, 1.0, v139
	v_add_f32_e32 v136, 1.0, v136
	v_rcp_f32_e32 v142, v139
	v_min_f32_e32 v139, 0x7149f2ca, v136
	v_add_f32_e32 v136, 1.0, v140
	v_lshlrev_b32_e32 v140, 16, v137
	v_and_b32_e32 v141, 0xffff0000, v141
	v_mul_f32_e32 v140, 0xbfb8aa3b, v140
	v_mul_f32_e32 v143, 0xbfb8aa3b, v143
	v_mul_f32_e32 v141, 0xbfb8aa3b, v141
	v_exp_f32_e32 v140, v140
	v_exp_f32_e32 v145, v143
	v_exp_f32_e32 v141, v141
	v_and_b32_e32 v137, 0xffff0000, v137
	v_mul_f32_e32 v137, 0xbfb8aa3b, v137
	v_exp_f32_e32 v137, v137
	v_rcp_f32_e32 v143, v136
	v_add_f32_e32 v136, 1.0, v140
	v_add_f32_e32 v140, 1.0, v145
	v_add_f32_e32 v141, 1.0, v141
	v_rcp_f32_e32 v140, v140
	v_rcp_f32_e32 v141, v141
	v_add_f32_e32 v137, 1.0, v137
	v_min_f32_e32 v136, 0x7149f2ca, v136
	v_min_f32_e32 v137, 0x7149f2ca, v137
	v_pk_mul_f32 v[136:137], v[136:137], v[140:141]
	v_mul_f32_e32 v138, 0xbfb8aa3b, v138
	v_pk_mul_f32 v[78:79], v[78:79], v[136:137]
	v_pk_mul_f32 v[148:149], v[148:149], v[150:151]
	v_exp_f32_e32 v138, v138
	v_pk_mul_f32 v[72:73], v[72:73], v[148:149]
	v_add_f32_e32 v138, 1.0, v138
	s_waitcnt vmcnt(1)
	v_lshlrev_b32_e32 v136, 16, v130
	v_mul_f32_e32 v136, 0xbfb8aa3b, v136
	v_exp_f32_e32 v136, v136
	s_waitcnt vmcnt(0)
	v_lshlrev_b32_e32 v137, 16, v134
	v_mul_f32_e32 v137, 0xbfb8aa3b, v137
	v_exp_f32_e32 v137, v137
	v_add_f32_e32 v136, 1.0, v136
	v_min_f32_e32 v148, 0x7149f2ca, v136
	v_or_b32_e32 v136, 48, v144
	v_add_f32_e32 v145, 1.0, v137
	v_mov_b32_e32 v137, v147
	v_lshlrev_b64 v[136:137], 10, v[136:137]
	v_lshl_add_u64 v[136:137], v[136:137], 0, v[146:147]
	v_lshlrev_b64 v[150:151], 1, v[136:137]
	v_min_f32_e32 v138, 0x7149f2ca, v138
	v_or_b32_e32 v140, 0x100, v150
	v_mov_b32_e32 v141, v151
	v_pk_mul_f32 v[138:139], v[138:139], v[142:143]
	v_lshl_add_u64 v[136:137], s[6:7], 0, v[140:141]
	v_pk_mul_f32 v[76:77], v[76:77], v[138:139]
	global_load_dwordx4 v[136:139], v[136:137], off
	v_lshl_add_u64 v[140:141], s[70:71], 0, v[140:141]
	global_load_dwordx4 v[140:143], v[140:141], off nt
	v_and_b32_e32 v130, 0xffff0000, v130
	v_mul_f32_e32 v130, 0xbfb8aa3b, v130
	v_and_b32_e32 v134, 0xffff0000, v134
	v_exp_f32_e32 v130, v130
	v_mul_f32_e32 v134, 0xbfb8aa3b, v134
	v_exp_f32_e32 v134, v134
	v_rcp_f32_e32 v152, v145
	v_add_f32_e32 v130, 1.0, v130
	v_min_f32_e32 v149, 0x7149f2ca, v130
	v_add_f32_e32 v130, 1.0, v134
	v_lshlrev_b32_e32 v134, 16, v131
	v_lshlrev_b32_e32 v145, 16, v135
	v_and_b32_e32 v135, 0xffff0000, v135
	v_mul_f32_e32 v134, 0xbfb8aa3b, v134
	v_mul_f32_e32 v145, 0xbfb8aa3b, v145
	v_mul_f32_e32 v135, 0xbfb8aa3b, v135
	v_exp_f32_e32 v134, v134
	v_exp_f32_e32 v145, v145
	v_exp_f32_e32 v135, v135
	v_and_b32_e32 v131, 0xffff0000, v131
	v_mul_f32_e32 v131, 0xbfb8aa3b, v131
	v_exp_f32_e32 v131, v131
	v_rcp_f32_e32 v153, v130
	v_add_f32_e32 v130, 1.0, v134
	v_add_f32_e32 v134, 1.0, v145
	v_add_f32_e32 v135, 1.0, v135
	v_rcp_f32_e32 v134, v134
	v_rcp_f32_e32 v135, v135
	v_add_f32_e32 v131, 1.0, v131
	v_min_f32_e32 v130, 0x7149f2ca, v130
	v_min_f32_e32 v131, 0x7149f2ca, v131
	v_pk_mul_f32 v[130:131], v[130:131], v[134:135]
	v_lshlrev_b32_e32 v135, 16, v133
	v_pk_mul_f32 v[94:95], v[94:95], v[130:131]
	v_lshlrev_b32_e32 v130, 16, v128
	v_lshlrev_b32_e32 v131, 16, v132
	v_and_b32_e32 v128, 0xffff0000, v128
	v_mul_f32_e32 v131, 0xbfb8aa3b, v131
	v_mul_f32_e32 v128, 0xbfb8aa3b, v128
	v_and_b32_e32 v132, 0xffff0000, v132
	v_exp_f32_e32 v131, v131
	v_exp_f32_e32 v128, v128
	v_mul_f32_e32 v132, 0xbfb8aa3b, v132
	v_exp_f32_e32 v132, v132
	v_add_f32_e32 v131, 1.0, v131
	v_add_f32_e32 v128, 1.0, v128
	v_rcp_f32_e32 v134, v131
	v_min_f32_e32 v131, 0x7149f2ca, v128
	v_add_f32_e32 v128, 1.0, v132
	v_lshlrev_b32_e32 v132, 16, v129
	v_and_b32_e32 v133, 0xffff0000, v133
	v_mul_f32_e32 v132, 0xbfb8aa3b, v132
	v_mul_f32_e32 v135, 0xbfb8aa3b, v135
	v_mul_f32_e32 v133, 0xbfb8aa3b, v133
	v_exp_f32_e32 v132, v132
	v_exp_f32_e32 v145, v135
	v_exp_f32_e32 v133, v133
	v_and_b32_e32 v129, 0xffff0000, v129
	v_mul_f32_e32 v129, 0xbfb8aa3b, v129
	v_exp_f32_e32 v129, v129
	v_rcp_f32_e32 v135, v128
	v_add_f32_e32 v128, 1.0, v132
	v_add_f32_e32 v132, 1.0, v145
	v_add_f32_e32 v133, 1.0, v133
	v_rcp_f32_e32 v132, v132
	v_rcp_f32_e32 v133, v133
	v_add_f32_e32 v129, 1.0, v129
	v_min_f32_e32 v128, 0x7149f2ca, v128
	v_min_f32_e32 v129, 0x7149f2ca, v129
	v_pk_mul_f32 v[128:129], v[128:129], v[132:133]
	v_mul_f32_e32 v130, 0xbfb8aa3b, v130
	v_pk_mul_f32 v[102:103], v[102:103], v[128:129]
	v_exp_f32_e32 v130, v130
	v_pk_mul_f32 v[148:149], v[148:149], v[152:153]
	v_add_f32_e32 v130, 1.0, v130
	s_waitcnt vmcnt(1)
	v_lshlrev_b32_e32 v128, 16, v138
	v_mul_f32_e32 v128, 0xbfb8aa3b, v128
	s_waitcnt vmcnt(0)
	v_lshlrev_b32_e32 v129, 16, v142
	v_exp_f32_e32 v128, v128
	v_mul_f32_e32 v129, 0xbfb8aa3b, v129
	v_exp_f32_e32 v129, v129
	v_min_f32_e32 v130, 0x7149f2ca, v130
	v_add_f32_e32 v128, 1.0, v128
	v_pk_mul_f32 v[92:93], v[92:93], v[148:149]
	v_pk_mul_f32 v[130:131], v[130:131], v[134:135]
	v_min_f32_e32 v148, 0x7149f2ca, v128
	v_add_f32_e32 v145, 1.0, v129
	v_and_b32_e32 v132, 0xffff0000, v138
	v_lshl_add_u64 v[128:129], s[6:7], 0, v[150:151]
	v_pk_mul_f32 v[100:101], v[100:101], v[130:131]
	global_load_dwordx4 v[128:131], v[128:129], off
	v_mul_f32_e32 v138, 0xbfb8aa3b, v132
	v_lshl_add_u64 v[132:133], s[70:71], 0, v[150:151]
	global_load_dwordx4 v[132:135], v[132:133], off nt
	v_and_b32_e32 v142, 0xffff0000, v142
	v_exp_f32_e32 v138, v138
	v_mul_f32_e32 v142, 0xbfb8aa3b, v142
	v_exp_f32_e32 v142, v142
	v_rcp_f32_e32 v150, v145
	v_add_f32_e32 v138, 1.0, v138
	v_min_f32_e32 v149, 0x7149f2ca, v138
	v_add_f32_e32 v138, 1.0, v142
	v_lshlrev_b32_e32 v142, 16, v139
	v_lshlrev_b32_e32 v145, 16, v143
	v_and_b32_e32 v143, 0xffff0000, v143
	v_mul_f32_e32 v142, 0xbfb8aa3b, v142
	v_mul_f32_e32 v145, 0xbfb8aa3b, v145
	v_mul_f32_e32 v143, 0xbfb8aa3b, v143
	v_exp_f32_e32 v142, v142
	v_exp_f32_e32 v145, v145
	v_exp_f32_e32 v143, v143
	v_and_b32_e32 v139, 0xffff0000, v139
	v_mul_f32_e32 v139, 0xbfb8aa3b, v139
	v_exp_f32_e32 v139, v139
	v_rcp_f32_e32 v151, v138
	v_add_f32_e32 v138, 1.0, v142
	v_add_f32_e32 v142, 1.0, v145
	v_add_f32_e32 v143, 1.0, v143
	v_rcp_f32_e32 v142, v142
	v_rcp_f32_e32 v143, v143
	v_add_f32_e32 v139, 1.0, v139
	v_min_f32_e32 v138, 0x7149f2ca, v138
	v_min_f32_e32 v139, 0x7149f2ca, v139
	v_pk_mul_f32 v[138:139], v[138:139], v[142:143]
	v_lshlrev_b32_e32 v143, 16, v141
	v_pk_mul_f32 v[114:115], v[114:115], v[138:139]
	v_lshlrev_b32_e32 v138, 16, v136
	v_lshlrev_b32_e32 v139, 16, v140
	v_and_b32_e32 v136, 0xffff0000, v136
	v_mul_f32_e32 v139, 0xbfb8aa3b, v139
	v_mul_f32_e32 v136, 0xbfb8aa3b, v136
	v_and_b32_e32 v140, 0xffff0000, v140
	v_exp_f32_e32 v139, v139
	v_exp_f32_e32 v136, v136
	v_mul_f32_e32 v140, 0xbfb8aa3b, v140
	v_exp_f32_e32 v140, v140
	v_add_f32_e32 v139, 1.0, v139
	v_add_f32_e32 v136, 1.0, v136
	v_rcp_f32_e32 v142, v139
	v_min_f32_e32 v139, 0x7149f2ca, v136
	v_add_f32_e32 v136, 1.0, v140
	v_lshlrev_b32_e32 v140, 16, v137
	v_and_b32_e32 v141, 0xffff0000, v141
	v_mul_f32_e32 v140, 0xbfb8aa3b, v140
	v_mul_f32_e32 v143, 0xbfb8aa3b, v143
	v_mul_f32_e32 v141, 0xbfb8aa3b, v141
	v_exp_f32_e32 v140, v140
	v_exp_f32_e32 v145, v143
	v_exp_f32_e32 v141, v141
	v_and_b32_e32 v137, 0xffff0000, v137
	v_mul_f32_e32 v137, 0xbfb8aa3b, v137
	v_exp_f32_e32 v137, v137
	v_rcp_f32_e32 v143, v136
	v_add_f32_e32 v136, 1.0, v140
	v_add_f32_e32 v140, 1.0, v145
	v_add_f32_e32 v141, 1.0, v141
	v_rcp_f32_e32 v140, v140
	v_rcp_f32_e32 v141, v141
	v_add_f32_e32 v137, 1.0, v137
	v_min_f32_e32 v136, 0x7149f2ca, v136
	v_min_f32_e32 v137, 0x7149f2ca, v137
	v_pk_mul_f32 v[136:137], v[136:137], v[140:141]
	v_mul_f32_e32 v138, 0xbfb8aa3b, v138
	v_pk_mul_f32 v[118:119], v[118:119], v[136:137]
	v_pk_mul_f32 v[148:149], v[148:149], v[150:151]
	v_exp_f32_e32 v138, v138
	v_pk_mul_f32 v[112:113], v[112:113], v[148:149]
	v_add_f32_e32 v138, 1.0, v138
	s_waitcnt vmcnt(1)
	v_lshlrev_b32_e32 v136, 16, v130
	v_mul_f32_e32 v136, 0xbfb8aa3b, v136
	v_exp_f32_e32 v136, v136
	s_waitcnt vmcnt(0)
	v_lshlrev_b32_e32 v137, 16, v134
	v_mul_f32_e32 v137, 0xbfb8aa3b, v137
	v_exp_f32_e32 v137, v137
	v_add_f32_e32 v136, 1.0, v136
	v_min_f32_e32 v148, 0x7149f2ca, v136
	v_or_b32_e32 v136, 32, v144
	v_add_f32_e32 v145, 1.0, v137
	v_mov_b32_e32 v137, v147
	v_lshlrev_b64 v[136:137], 10, v[136:137]
	v_lshl_add_u64 v[136:137], v[136:137], 0, v[146:147]
	v_lshlrev_b64 v[150:151], 1, v[136:137]
	v_min_f32_e32 v138, 0x7149f2ca, v138
	v_or_b32_e32 v140, 0x100, v150
	v_mov_b32_e32 v141, v151
	v_pk_mul_f32 v[138:139], v[138:139], v[142:143]
	v_lshl_add_u64 v[136:137], s[6:7], 0, v[140:141]
	v_pk_mul_f32 v[116:117], v[116:117], v[138:139]
	global_load_dwordx4 v[136:139], v[136:137], off
	v_lshl_add_u64 v[140:141], s[70:71], 0, v[140:141]
	global_load_dwordx4 v[140:143], v[140:141], off nt
	v_and_b32_e32 v130, 0xffff0000, v130
	v_mul_f32_e32 v130, 0xbfb8aa3b, v130
	v_and_b32_e32 v134, 0xffff0000, v134
	v_exp_f32_e32 v130, v130
	v_mul_f32_e32 v134, 0xbfb8aa3b, v134
	v_exp_f32_e32 v134, v134
	v_rcp_f32_e32 v152, v145
	v_add_f32_e32 v130, 1.0, v130
	v_min_f32_e32 v149, 0x7149f2ca, v130
	v_add_f32_e32 v130, 1.0, v134
	v_lshlrev_b32_e32 v134, 16, v131
	v_lshlrev_b32_e32 v145, 16, v135
	v_and_b32_e32 v135, 0xffff0000, v135
	v_mul_f32_e32 v134, 0xbfb8aa3b, v134
	v_mul_f32_e32 v145, 0xbfb8aa3b, v145
	v_mul_f32_e32 v135, 0xbfb8aa3b, v135
	v_exp_f32_e32 v134, v134
	v_exp_f32_e32 v145, v145
	v_exp_f32_e32 v135, v135
	v_and_b32_e32 v131, 0xffff0000, v131
	v_mul_f32_e32 v131, 0xbfb8aa3b, v131
	v_exp_f32_e32 v131, v131
	v_rcp_f32_e32 v153, v130
	v_add_f32_e32 v130, 1.0, v134
	v_add_f32_e32 v134, 1.0, v145
	v_add_f32_e32 v135, 1.0, v135
	v_rcp_f32_e32 v134, v134
	v_rcp_f32_e32 v135, v135
	v_add_f32_e32 v131, 1.0, v131
	v_min_f32_e32 v130, 0x7149f2ca, v130
	v_min_f32_e32 v131, 0x7149f2ca, v131
	v_pk_mul_f32 v[130:131], v[130:131], v[134:135]
	v_lshlrev_b32_e32 v135, 16, v133
	v_pk_mul_f32 v[126:127], v[126:127], v[130:131]
	v_lshlrev_b32_e32 v130, 16, v128
	v_lshlrev_b32_e32 v131, 16, v132
	v_and_b32_e32 v128, 0xffff0000, v128
	v_mul_f32_e32 v131, 0xbfb8aa3b, v131
	v_mul_f32_e32 v128, 0xbfb8aa3b, v128
	v_and_b32_e32 v132, 0xffff0000, v132
	v_exp_f32_e32 v131, v131
	v_exp_f32_e32 v128, v128
	v_mul_f32_e32 v132, 0xbfb8aa3b, v132
	v_exp_f32_e32 v132, v132
	v_add_f32_e32 v131, 1.0, v131
	v_add_f32_e32 v128, 1.0, v128
	v_rcp_f32_e32 v134, v131
	v_min_f32_e32 v131, 0x7149f2ca, v128
	v_add_f32_e32 v128, 1.0, v132
	v_lshlrev_b32_e32 v132, 16, v129
	v_and_b32_e32 v133, 0xffff0000, v133
	v_mul_f32_e32 v132, 0xbfb8aa3b, v132
	v_mul_f32_e32 v135, 0xbfb8aa3b, v135
	v_mul_f32_e32 v133, 0xbfb8aa3b, v133
	v_exp_f32_e32 v132, v132
	v_exp_f32_e32 v145, v135
	v_exp_f32_e32 v133, v133
	v_and_b32_e32 v129, 0xffff0000, v129
	v_mul_f32_e32 v129, 0xbfb8aa3b, v129
	v_exp_f32_e32 v129, v129
	v_rcp_f32_e32 v135, v128
	v_add_f32_e32 v128, 1.0, v132
	v_add_f32_e32 v132, 1.0, v145
	v_add_f32_e32 v133, 1.0, v133
	v_rcp_f32_e32 v132, v132
	v_rcp_f32_e32 v133, v133
	v_add_f32_e32 v129, 1.0, v129
	v_min_f32_e32 v128, 0x7149f2ca, v128
	v_min_f32_e32 v129, 0x7149f2ca, v129
	v_pk_mul_f32 v[128:129], v[128:129], v[132:133]
	v_mul_f32_e32 v130, 0xbfb8aa3b, v130
	v_pk_mul_f32 v[122:123], v[122:123], v[128:129]
	v_exp_f32_e32 v130, v130
	v_pk_mul_f32 v[148:149], v[148:149], v[152:153]
	v_add_f32_e32 v130, 1.0, v130
	s_waitcnt vmcnt(1)
	v_lshlrev_b32_e32 v128, 16, v138
	v_mul_f32_e32 v128, 0xbfb8aa3b, v128
	s_waitcnt vmcnt(0)
	v_lshlrev_b32_e32 v129, 16, v142
	v_exp_f32_e32 v128, v128
	v_mul_f32_e32 v129, 0xbfb8aa3b, v129
	v_exp_f32_e32 v129, v129
	v_min_f32_e32 v130, 0x7149f2ca, v130
	v_add_f32_e32 v128, 1.0, v128
	v_pk_mul_f32 v[124:125], v[124:125], v[148:149]
	v_pk_mul_f32 v[130:131], v[130:131], v[134:135]
	v_min_f32_e32 v148, 0x7149f2ca, v128
	v_add_f32_e32 v145, 1.0, v129
	v_and_b32_e32 v132, 0xffff0000, v138
	v_lshl_add_u64 v[128:129], s[6:7], 0, v[150:151]
	v_pk_mul_f32 v[120:121], v[120:121], v[130:131]
	global_load_dwordx4 v[128:131], v[128:129], off
	v_mul_f32_e32 v138, 0xbfb8aa3b, v132
	v_lshl_add_u64 v[132:133], s[70:71], 0, v[150:151]
	global_load_dwordx4 v[132:135], v[132:133], off nt
	v_and_b32_e32 v142, 0xffff0000, v142
	v_exp_f32_e32 v138, v138
	v_mul_f32_e32 v142, 0xbfb8aa3b, v142
	v_exp_f32_e32 v142, v142
	v_rcp_f32_e32 v150, v145
	v_add_f32_e32 v138, 1.0, v138
	v_min_f32_e32 v149, 0x7149f2ca, v138
	v_add_f32_e32 v138, 1.0, v142
	v_lshlrev_b32_e32 v142, 16, v139
	v_lshlrev_b32_e32 v145, 16, v143
	v_and_b32_e32 v143, 0xffff0000, v143
	v_mul_f32_e32 v142, 0xbfb8aa3b, v142
	v_mul_f32_e32 v145, 0xbfb8aa3b, v145
	v_mul_f32_e32 v143, 0xbfb8aa3b, v143
	v_exp_f32_e32 v142, v142
	v_exp_f32_e32 v145, v145
	v_exp_f32_e32 v143, v143
	v_and_b32_e32 v139, 0xffff0000, v139
	v_mul_f32_e32 v139, 0xbfb8aa3b, v139
	v_exp_f32_e32 v139, v139
	v_rcp_f32_e32 v151, v138
	v_add_f32_e32 v138, 1.0, v142
	v_add_f32_e32 v142, 1.0, v145
	v_add_f32_e32 v143, 1.0, v143
	v_rcp_f32_e32 v142, v142
	v_rcp_f32_e32 v143, v143
	v_add_f32_e32 v139, 1.0, v139
	v_min_f32_e32 v138, 0x7149f2ca, v138
	v_min_f32_e32 v139, 0x7149f2ca, v139
	v_pk_mul_f32 v[138:139], v[138:139], v[142:143]
	v_lshlrev_b32_e32 v143, 16, v141
	v_pk_mul_f32 v[110:111], v[110:111], v[138:139]
	v_lshlrev_b32_e32 v138, 16, v136
	v_lshlrev_b32_e32 v139, 16, v140
	v_and_b32_e32 v136, 0xffff0000, v136
	v_mul_f32_e32 v139, 0xbfb8aa3b, v139
	v_mul_f32_e32 v136, 0xbfb8aa3b, v136
	v_and_b32_e32 v140, 0xffff0000, v140
	v_exp_f32_e32 v139, v139
	v_exp_f32_e32 v136, v136
	v_mul_f32_e32 v140, 0xbfb8aa3b, v140
	v_exp_f32_e32 v140, v140
	v_add_f32_e32 v139, 1.0, v139
	v_add_f32_e32 v136, 1.0, v136
	v_rcp_f32_e32 v142, v139
	v_min_f32_e32 v139, 0x7149f2ca, v136
	v_add_f32_e32 v136, 1.0, v140
	v_lshlrev_b32_e32 v140, 16, v137
	v_and_b32_e32 v141, 0xffff0000, v141
	v_mul_f32_e32 v140, 0xbfb8aa3b, v140
	v_mul_f32_e32 v143, 0xbfb8aa3b, v143
	v_mul_f32_e32 v141, 0xbfb8aa3b, v141
	v_exp_f32_e32 v140, v140
	v_exp_f32_e32 v145, v143
	v_exp_f32_e32 v141, v141
	v_and_b32_e32 v137, 0xffff0000, v137
	v_mul_f32_e32 v137, 0xbfb8aa3b, v137
	v_exp_f32_e32 v137, v137
	v_rcp_f32_e32 v143, v136
	v_add_f32_e32 v136, 1.0, v140
	v_add_f32_e32 v140, 1.0, v145
	v_add_f32_e32 v141, 1.0, v141
	v_rcp_f32_e32 v140, v140
	v_rcp_f32_e32 v141, v141
	v_add_f32_e32 v137, 1.0, v137
	v_min_f32_e32 v136, 0x7149f2ca, v136
	v_min_f32_e32 v137, 0x7149f2ca, v137
	v_pk_mul_f32 v[136:137], v[136:137], v[140:141]
	v_mul_f32_e32 v138, 0xbfb8aa3b, v138
	v_pk_mul_f32 v[106:107], v[106:107], v[136:137]
	v_pk_mul_f32 v[148:149], v[148:149], v[150:151]
	v_exp_f32_e32 v138, v138
	v_pk_mul_f32 v[108:109], v[108:109], v[148:149]
	v_add_f32_e32 v138, 1.0, v138
	s_waitcnt vmcnt(1)
	v_lshlrev_b32_e32 v136, 16, v130
	v_mul_f32_e32 v136, 0xbfb8aa3b, v136
	v_exp_f32_e32 v136, v136
	s_waitcnt vmcnt(0)
	v_lshlrev_b32_e32 v137, 16, v134
	v_mul_f32_e32 v137, 0xbfb8aa3b, v137
	v_exp_f32_e32 v137, v137
	v_add_f32_e32 v136, 1.0, v136
	v_min_f32_e32 v148, 0x7149f2ca, v136
	v_or_b32_e32 v136, 16, v144
	v_add_f32_e32 v145, 1.0, v137
	v_mov_b32_e32 v137, v147
	v_lshlrev_b64 v[136:137], 10, v[136:137]
	v_lshl_add_u64 v[136:137], v[136:137], 0, v[146:147]
	v_lshlrev_b64 v[150:151], 1, v[136:137]
	v_min_f32_e32 v138, 0x7149f2ca, v138
	v_or_b32_e32 v140, 0x100, v150
	v_mov_b32_e32 v141, v151
	v_pk_mul_f32 v[138:139], v[138:139], v[142:143]
	v_lshl_add_u64 v[136:137], s[6:7], 0, v[140:141]
	v_pk_mul_f32 v[104:105], v[104:105], v[138:139]
	global_load_dwordx4 v[136:139], v[136:137], off
	v_lshl_add_u64 v[140:141], s[70:71], 0, v[140:141]
	global_load_dwordx4 v[140:143], v[140:141], off nt
	v_and_b32_e32 v130, 0xffff0000, v130
	v_mul_f32_e32 v130, 0xbfb8aa3b, v130
	v_and_b32_e32 v134, 0xffff0000, v134
	v_exp_f32_e32 v130, v130
	v_mul_f32_e32 v134, 0xbfb8aa3b, v134
	v_exp_f32_e32 v134, v134
	v_rcp_f32_e32 v152, v145
	v_add_f32_e32 v130, 1.0, v130
	v_min_f32_e32 v149, 0x7149f2ca, v130
	v_add_f32_e32 v130, 1.0, v134
	v_lshlrev_b32_e32 v134, 16, v131
	v_lshlrev_b32_e32 v145, 16, v135
	v_and_b32_e32 v135, 0xffff0000, v135
	v_mul_f32_e32 v134, 0xbfb8aa3b, v134
	v_mul_f32_e32 v145, 0xbfb8aa3b, v145
	v_mul_f32_e32 v135, 0xbfb8aa3b, v135
	v_exp_f32_e32 v134, v134
	v_exp_f32_e32 v145, v145
	v_exp_f32_e32 v135, v135
	v_and_b32_e32 v131, 0xffff0000, v131
	v_mul_f32_e32 v131, 0xbfb8aa3b, v131
	v_exp_f32_e32 v131, v131
	v_rcp_f32_e32 v153, v130
	v_add_f32_e32 v130, 1.0, v134
	v_add_f32_e32 v134, 1.0, v145
	v_add_f32_e32 v135, 1.0, v135
	v_rcp_f32_e32 v134, v134
	v_rcp_f32_e32 v135, v135
	v_add_f32_e32 v131, 1.0, v131
	v_min_f32_e32 v130, 0x7149f2ca, v130
	v_min_f32_e32 v131, 0x7149f2ca, v131
	v_pk_mul_f32 v[130:131], v[130:131], v[134:135]
	v_lshlrev_b32_e32 v135, 16, v133
	v_pk_mul_f32 v[98:99], v[98:99], v[130:131]
	v_lshlrev_b32_e32 v130, 16, v128
	v_lshlrev_b32_e32 v131, 16, v132
	v_and_b32_e32 v128, 0xffff0000, v128
	v_mul_f32_e32 v131, 0xbfb8aa3b, v131
	v_mul_f32_e32 v128, 0xbfb8aa3b, v128
	v_and_b32_e32 v132, 0xffff0000, v132
	v_exp_f32_e32 v131, v131
	v_exp_f32_e32 v128, v128
	v_mul_f32_e32 v132, 0xbfb8aa3b, v132
	v_exp_f32_e32 v132, v132
	v_add_f32_e32 v131, 1.0, v131
	v_add_f32_e32 v128, 1.0, v128
	v_rcp_f32_e32 v134, v131
	v_min_f32_e32 v131, 0x7149f2ca, v128
	v_add_f32_e32 v128, 1.0, v132
	v_lshlrev_b32_e32 v132, 16, v129
	v_and_b32_e32 v133, 0xffff0000, v133
	v_mul_f32_e32 v132, 0xbfb8aa3b, v132
	v_mul_f32_e32 v135, 0xbfb8aa3b, v135
	v_mul_f32_e32 v133, 0xbfb8aa3b, v133
	v_exp_f32_e32 v132, v132
	v_exp_f32_e32 v145, v135
	v_exp_f32_e32 v133, v133
	v_and_b32_e32 v129, 0xffff0000, v129
	v_mul_f32_e32 v129, 0xbfb8aa3b, v129
	v_exp_f32_e32 v129, v129
	v_rcp_f32_e32 v135, v128
	v_add_f32_e32 v128, 1.0, v132
	v_add_f32_e32 v132, 1.0, v145
	v_add_f32_e32 v133, 1.0, v133
	v_rcp_f32_e32 v132, v132
	v_rcp_f32_e32 v133, v133
	v_add_f32_e32 v129, 1.0, v129
	v_min_f32_e32 v128, 0x7149f2ca, v128
	v_min_f32_e32 v129, 0x7149f2ca, v129
	v_pk_mul_f32 v[128:129], v[128:129], v[132:133]
	v_mul_f32_e32 v130, 0xbfb8aa3b, v130
	v_pk_mul_f32 v[90:91], v[90:91], v[128:129]
	v_exp_f32_e32 v130, v130
	v_pk_mul_f32 v[148:149], v[148:149], v[152:153]
	v_add_f32_e32 v130, 1.0, v130
	s_waitcnt vmcnt(1)
	v_lshlrev_b32_e32 v128, 16, v138
	v_mul_f32_e32 v128, 0xbfb8aa3b, v128
	s_waitcnt vmcnt(0)
	v_lshlrev_b32_e32 v129, 16, v142
	v_exp_f32_e32 v128, v128
	v_mul_f32_e32 v129, 0xbfb8aa3b, v129
	v_exp_f32_e32 v129, v129
	v_min_f32_e32 v130, 0x7149f2ca, v130
	v_add_f32_e32 v128, 1.0, v128
	v_pk_mul_f32 v[96:97], v[96:97], v[148:149]
	v_pk_mul_f32 v[130:131], v[130:131], v[134:135]
	v_min_f32_e32 v148, 0x7149f2ca, v128
	v_add_f32_e32 v145, 1.0, v129
	v_and_b32_e32 v132, 0xffff0000, v138
	v_lshl_add_u64 v[128:129], s[6:7], 0, v[150:151]
	v_pk_mul_f32 v[88:89], v[88:89], v[130:131]
	global_load_dwordx4 v[128:131], v[128:129], off
	v_mul_f32_e32 v138, 0xbfb8aa3b, v132
	v_lshl_add_u64 v[132:133], s[70:71], 0, v[150:151]
	global_load_dwordx4 v[132:135], v[132:133], off nt
	v_and_b32_e32 v142, 0xffff0000, v142
	v_exp_f32_e32 v138, v138
	v_mul_f32_e32 v142, 0xbfb8aa3b, v142
	v_exp_f32_e32 v142, v142
	v_rcp_f32_e32 v150, v145
	v_add_f32_e32 v138, 1.0, v138
	v_min_f32_e32 v149, 0x7149f2ca, v138
	v_add_f32_e32 v138, 1.0, v142
	v_lshlrev_b32_e32 v142, 16, v139
	v_lshlrev_b32_e32 v145, 16, v143
	v_and_b32_e32 v143, 0xffff0000, v143
	v_mul_f32_e32 v142, 0xbfb8aa3b, v142
	v_mul_f32_e32 v145, 0xbfb8aa3b, v145
	v_mul_f32_e32 v143, 0xbfb8aa3b, v143
	v_exp_f32_e32 v142, v142
	v_exp_f32_e32 v145, v145
	v_exp_f32_e32 v143, v143
	v_and_b32_e32 v139, 0xffff0000, v139
	v_mul_f32_e32 v139, 0xbfb8aa3b, v139
	v_exp_f32_e32 v139, v139
	v_rcp_f32_e32 v151, v138
	v_add_f32_e32 v138, 1.0, v142
	v_add_f32_e32 v142, 1.0, v145
	v_add_f32_e32 v143, 1.0, v143
	v_rcp_f32_e32 v142, v142
	v_rcp_f32_e32 v143, v143
	v_add_f32_e32 v139, 1.0, v139
	v_min_f32_e32 v138, 0x7149f2ca, v138
	v_min_f32_e32 v139, 0x7149f2ca, v139
	v_pk_mul_f32 v[138:139], v[138:139], v[142:143]
	v_lshlrev_b32_e32 v143, 16, v141
	v_pk_mul_f32 v[86:87], v[86:87], v[138:139]
	v_lshlrev_b32_e32 v138, 16, v136
	v_lshlrev_b32_e32 v139, 16, v140
	v_and_b32_e32 v136, 0xffff0000, v136
	v_mul_f32_e32 v139, 0xbfb8aa3b, v139
	v_mul_f32_e32 v136, 0xbfb8aa3b, v136
	v_and_b32_e32 v140, 0xffff0000, v140
	v_exp_f32_e32 v139, v139
	v_exp_f32_e32 v136, v136
	v_mul_f32_e32 v140, 0xbfb8aa3b, v140
	v_exp_f32_e32 v140, v140
	v_add_f32_e32 v139, 1.0, v139
	v_add_f32_e32 v136, 1.0, v136
	v_rcp_f32_e32 v142, v139
	v_min_f32_e32 v139, 0x7149f2ca, v136
	v_add_f32_e32 v136, 1.0, v140
	v_lshlrev_b32_e32 v140, 16, v137
	v_and_b32_e32 v141, 0xffff0000, v141
	v_mul_f32_e32 v140, 0xbfb8aa3b, v140
	v_mul_f32_e32 v143, 0xbfb8aa3b, v143
	v_mul_f32_e32 v141, 0xbfb8aa3b, v141
	v_exp_f32_e32 v140, v140
	v_exp_f32_e32 v145, v143
	v_exp_f32_e32 v141, v141
	v_and_b32_e32 v137, 0xffff0000, v137
	v_mul_f32_e32 v137, 0xbfb8aa3b, v137
	v_exp_f32_e32 v137, v137
	v_rcp_f32_e32 v143, v136
	v_add_f32_e32 v136, 1.0, v140
	v_add_f32_e32 v140, 1.0, v145
	v_add_f32_e32 v141, 1.0, v141
	v_rcp_f32_e32 v140, v140
	v_rcp_f32_e32 v141, v141
	v_add_f32_e32 v137, 1.0, v137
	v_min_f32_e32 v136, 0x7149f2ca, v136
	v_min_f32_e32 v137, 0x7149f2ca, v137
	v_pk_mul_f32 v[136:137], v[136:137], v[140:141]
	v_mul_f32_e32 v138, 0xbfb8aa3b, v138
	v_pk_mul_f32 v[82:83], v[82:83], v[136:137]
	v_pk_mul_f32 v[148:149], v[148:149], v[150:151]
	v_exp_f32_e32 v138, v138
	v_mov_b32_e32 v145, v147
	v_pk_mul_f32 v[84:85], v[84:85], v[148:149]
	v_add_f32_e32 v138, 1.0, v138
	s_waitcnt vmcnt(1)
	v_lshlrev_b32_e32 v136, 16, v130
	v_mul_f32_e32 v136, 0xbfb8aa3b, v136
	v_exp_f32_e32 v136, v136
	s_waitcnt vmcnt(0)
	v_lshlrev_b32_e32 v137, 16, v134
	v_mul_f32_e32 v137, 0xbfb8aa3b, v137
	v_exp_f32_e32 v137, v137
	v_add_f32_e32 v136, 1.0, v136
	v_min_f32_e32 v148, 0x7149f2ca, v136
	v_min_f32_e32 v138, 0x7149f2ca, v138
	v_add_f32_e32 v149, 1.0, v137
	v_lshlrev_b64 v[136:137], 10, v[144:145]
	v_lshl_add_u64 v[136:137], v[136:137], 0, v[146:147]
	v_lshlrev_b64 v[144:145], 1, v[136:137]
	v_or_b32_e32 v140, 0x100, v144
	v_mov_b32_e32 v141, v145
	v_lshl_add_u64 v[136:137], s[6:7], 0, v[140:141]
	v_lshl_add_u64 v[140:141], s[70:71], 0, v[140:141]
	v_pk_mul_f32 v[138:139], v[138:139], v[142:143]
	global_load_dwordx4 v[140:143], v[140:141], off nt
	v_pk_mul_f32 v[80:81], v[80:81], v[138:139]
	global_load_dwordx4 v[136:139], v[136:137], off
	v_and_b32_e32 v130, 0xffff0000, v130
	v_mul_f32_e32 v130, 0xbfb8aa3b, v130
	v_and_b32_e32 v134, 0xffff0000, v134
	v_exp_f32_e32 v130, v130
	v_mul_f32_e32 v134, 0xbfb8aa3b, v134
	v_exp_f32_e32 v134, v134
	v_rcp_f32_e32 v146, v149
	v_add_f32_e32 v130, 1.0, v130
	v_min_f32_e32 v149, 0x7149f2ca, v130
	v_add_f32_e32 v130, 1.0, v134
	v_lshlrev_b32_e32 v134, 16, v131
	v_lshlrev_b32_e32 v147, 16, v135
	v_and_b32_e32 v135, 0xffff0000, v135
	v_mul_f32_e32 v134, 0xbfb8aa3b, v134
	v_mul_f32_e32 v147, 0xbfb8aa3b, v147
	v_mul_f32_e32 v135, 0xbfb8aa3b, v135
	v_exp_f32_e32 v134, v134
	v_exp_f32_e32 v150, v147
	v_exp_f32_e32 v135, v135
	v_and_b32_e32 v131, 0xffff0000, v131
	v_mul_f32_e32 v131, 0xbfb8aa3b, v131
	v_exp_f32_e32 v131, v131
	v_rcp_f32_e32 v147, v130
	v_add_f32_e32 v130, 1.0, v134
	v_add_f32_e32 v134, 1.0, v150
	v_add_f32_e32 v135, 1.0, v135
	v_rcp_f32_e32 v134, v134
	v_rcp_f32_e32 v135, v135
	v_add_f32_e32 v131, 1.0, v131
	v_min_f32_e32 v130, 0x7149f2ca, v130
	v_min_f32_e32 v131, 0x7149f2ca, v131
	v_pk_mul_f32 v[130:131], v[130:131], v[134:135]
	v_lshlrev_b32_e32 v135, 16, v133
	v_pk_mul_f32 v[70:71], v[70:71], v[130:131]
	v_lshlrev_b32_e32 v130, 16, v128
	v_lshlrev_b32_e32 v131, 16, v132
	v_and_b32_e32 v128, 0xffff0000, v128
	v_mul_f32_e32 v131, 0xbfb8aa3b, v131
	v_mul_f32_e32 v128, 0xbfb8aa3b, v128
	v_and_b32_e32 v132, 0xffff0000, v132
	v_exp_f32_e32 v131, v131
	v_exp_f32_e32 v128, v128
	v_mul_f32_e32 v132, 0xbfb8aa3b, v132
	v_exp_f32_e32 v132, v132
	v_add_f32_e32 v131, 1.0, v131
	v_add_f32_e32 v128, 1.0, v128
	v_rcp_f32_e32 v134, v131
	v_min_f32_e32 v131, 0x7149f2ca, v128
	v_add_f32_e32 v128, 1.0, v132
	v_lshlrev_b32_e32 v132, 16, v129
	v_and_b32_e32 v133, 0xffff0000, v133
	v_pk_mul_f32 v[146:147], v[148:149], v[146:147]
	v_mul_f32_e32 v132, 0xbfb8aa3b, v132
	v_mul_f32_e32 v135, 0xbfb8aa3b, v135
	v_mul_f32_e32 v133, 0xbfb8aa3b, v133
	v_mul_f32_e32 v130, 0xbfb8aa3b, v130
	v_pk_mul_f32 v[68:69], v[68:69], v[146:147]
	v_exp_f32_e32 v132, v132
	v_exp_f32_e32 v146, v135
	v_exp_f32_e32 v133, v133
	v_exp_f32_e32 v130, v130
	v_and_b32_e32 v129, 0xffff0000, v129
	v_mul_f32_e32 v129, 0xbfb8aa3b, v129
	v_rcp_f32_e32 v135, v128
	v_exp_f32_e32 v129, v129
	v_add_f32_e32 v128, 1.0, v132
	v_add_f32_e32 v132, 1.0, v146
	v_add_f32_e32 v133, 1.0, v133
	v_add_f32_e32 v130, 1.0, v130
	v_rcp_f32_e32 v132, v132
	v_rcp_f32_e32 v133, v133
	v_min_f32_e32 v130, 0x7149f2ca, v130
	v_add_f32_e32 v129, 1.0, v129
	v_pk_mul_f32 v[130:131], v[130:131], v[134:135]
	v_min_f32_e32 v128, 0x7149f2ca, v128
	v_min_f32_e32 v129, 0x7149f2ca, v129
	v_pk_mul_f32 v[64:65], v[64:65], v[130:131]
	v_lshl_add_u64 v[130:131], s[6:7], 0, v[144:145]
	v_pk_mul_f32 v[128:129], v[128:129], v[132:133]
	global_load_dwordx4 v[132:135], v[130:131], off nt
	v_lshl_add_u64 v[130:131], s[70:71], 0, v[144:145]
	global_load_dwordx4 v[144:147], v[130:131], off
	v_pk_mul_f32 v[66:67], v[66:67], v[128:129]
	s_waitcnt vmcnt(3)
	v_lshlrev_b32_e32 v129, 16, v142
	s_waitcnt vmcnt(2)
	v_lshlrev_b32_e32 v128, 16, v138
	v_mul_f32_e32 v129, 0xbfb8aa3b, v129
	v_and_b32_e32 v138, 0xffff0000, v138
	v_and_b32_e32 v130, 0xffff0000, v142
	v_exp_f32_e32 v129, v129
	v_mul_f32_e32 v138, 0xbfb8aa3b, v138
	v_mul_f32_e32 v130, 0xbfb8aa3b, v130
	v_exp_f32_e32 v131, v138
	v_exp_f32_e32 v138, v130
	v_lshlrev_b32_e32 v142, 16, v143
	v_and_b32_e32 v143, 0xffff0000, v143
	v_mul_f32_e32 v142, 0xbfb8aa3b, v142
	v_mul_f32_e32 v143, 0xbfb8aa3b, v143
	v_add_f32_e32 v129, 1.0, v129
	v_exp_f32_e32 v142, v142
	v_exp_f32_e32 v143, v143
	v_rcp_f32_e32 v130, v129
	v_add_f32_e32 v129, 1.0, v131
	v_add_f32_e32 v131, 1.0, v138
	v_lshlrev_b32_e32 v138, 16, v139
	v_and_b32_e32 v139, 0xffff0000, v139
	v_mul_f32_e32 v128, 0xbfb8aa3b, v128
	v_mul_f32_e32 v138, 0xbfb8aa3b, v138
	v_mul_f32_e32 v139, 0xbfb8aa3b, v139
	v_exp_f32_e32 v128, v128
	v_exp_f32_e32 v138, v138
	v_exp_f32_e32 v139, v139
	v_add_f32_e32 v142, 1.0, v142
	v_add_f32_e32 v143, 1.0, v143
	v_rcp_f32_e32 v131, v131
	v_rcp_f32_e32 v142, v142
	v_rcp_f32_e32 v143, v143
	v_add_f32_e32 v128, 1.0, v128
	v_add_f32_e32 v138, 1.0, v138
	v_add_f32_e32 v139, 1.0, v139
	v_min_f32_e32 v128, 0x7149f2ca, v128
	v_min_f32_e32 v129, 0x7149f2ca, v129
	v_min_f32_e32 v138, 0x7149f2ca, v138
	v_min_f32_e32 v139, 0x7149f2ca, v139
	v_pk_mul_f32 v[128:129], v[128:129], v[130:131]
	v_pk_mul_f32 v[130:131], v[138:139], v[142:143]
	v_pk_mul_f32 v[56:57], v[56:57], v[128:129]
	v_pk_mul_f32 v[58:59], v[58:59], v[130:131]
	v_lshlrev_b32_e32 v130, 16, v136
	v_mul_f32_e32 v130, 0xbfb8aa3b, v130
	v_exp_f32_e32 v130, v130
	v_lshlrev_b32_e32 v131, 16, v140
	v_mul_f32_e32 v131, 0xbfb8aa3b, v131
	v_exp_f32_e32 v131, v131
	v_add_f32_e32 v128, 1.0, v130
	v_and_b32_e32 v130, 0xffff0000, v136
	v_mul_f32_e32 v130, 0xbfb8aa3b, v130
	v_add_f32_e32 v129, 1.0, v131
	v_exp_f32_e32 v131, v130
	v_and_b32_e32 v130, 0xffff0000, v140
	v_mul_f32_e32 v130, 0xbfb8aa3b, v130
	v_exp_f32_e32 v136, v130
	v_lshlrev_b32_e32 v138, 16, v141
	v_and_b32_e32 v139, 0xffff0000, v141
	v_mul_f32_e32 v138, 0xbfb8aa3b, v138
	v_mul_f32_e32 v139, 0xbfb8aa3b, v139
	v_exp_f32_e32 v138, v138
	v_exp_f32_e32 v139, v139
	v_rcp_f32_e32 v130, v129
	v_add_f32_e32 v129, 1.0, v131
	v_add_f32_e32 v131, 1.0, v136
	v_lshlrev_b32_e32 v136, 16, v137
	v_and_b32_e32 v137, 0xffff0000, v137
	v_mul_f32_e32 v136, 0xbfb8aa3b, v136
	v_mul_f32_e32 v137, 0xbfb8aa3b, v137
	v_exp_f32_e32 v136, v136
	v_exp_f32_e32 v137, v137
	v_add_f32_e32 v138, 1.0, v138
	v_add_f32_e32 v139, 1.0, v139
	v_rcp_f32_e32 v131, v131
	v_rcp_f32_e32 v138, v138
	v_rcp_f32_e32 v139, v139
	v_add_f32_e32 v136, 1.0, v136
	v_add_f32_e32 v137, 1.0, v137
	v_min_f32_e32 v128, 0x7149f2ca, v128
	v_min_f32_e32 v129, 0x7149f2ca, v129
	v_min_f32_e32 v136, 0x7149f2ca, v136
	v_min_f32_e32 v137, 0x7149f2ca, v137
	v_pk_mul_f32 v[128:129], v[128:129], v[130:131]
	v_pk_mul_f32 v[130:131], v[136:137], v[138:139]
	v_pk_mul_f32 v[128:129], v[48:49], v[128:129]
	v_pk_mul_f32 v[130:131], v[50:51], v[130:131]
	s_waitcnt vmcnt(1)
	v_lshlrev_b32_e32 v50, 16, v134
	v_mul_f32_e32 v50, 0xbfb8aa3b, v50
	v_exp_f32_e32 v50, v50
	s_waitcnt vmcnt(0)
	v_lshlrev_b32_e32 v51, 16, v146
	v_mul_f32_e32 v51, 0xbfb8aa3b, v51
	v_exp_f32_e32 v51, v51
	v_add_f32_e32 v48, 1.0, v50
	v_and_b32_e32 v50, 0xffff0000, v134
	v_mul_f32_e32 v50, 0xbfb8aa3b, v50
	v_add_f32_e32 v49, 1.0, v51
	v_exp_f32_e32 v51, v50
	v_and_b32_e32 v50, 0xffff0000, v146
	v_mul_f32_e32 v50, 0xbfb8aa3b, v50
	v_exp_f32_e32 v134, v50
	v_lshlrev_b32_e32 v136, 16, v147
	v_and_b32_e32 v137, 0xffff0000, v147
	v_mul_f32_e32 v136, 0xbfb8aa3b, v136
	v_mul_f32_e32 v137, 0xbfb8aa3b, v137
	v_exp_f32_e32 v136, v136
	v_exp_f32_e32 v137, v137
	v_rcp_f32_e32 v50, v49
	v_add_f32_e32 v49, 1.0, v51
	v_add_f32_e32 v51, 1.0, v134
	v_lshlrev_b32_e32 v134, 16, v135
	v_and_b32_e32 v135, 0xffff0000, v135
	v_mul_f32_e32 v134, 0xbfb8aa3b, v134
	v_mul_f32_e32 v135, 0xbfb8aa3b, v135
	v_exp_f32_e32 v134, v134
	v_exp_f32_e32 v135, v135
	v_add_f32_e32 v136, 1.0, v136
	v_add_f32_e32 v137, 1.0, v137
	v_rcp_f32_e32 v51, v51
	v_rcp_f32_e32 v136, v136
	v_rcp_f32_e32 v137, v137
	v_add_f32_e32 v134, 1.0, v134
	v_add_f32_e32 v135, 1.0, v135
	v_min_f32_e32 v48, 0x7149f2ca, v48
	v_min_f32_e32 v49, 0x7149f2ca, v49
	v_min_f32_e32 v134, 0x7149f2ca, v134
	v_min_f32_e32 v135, 0x7149f2ca, v135
	v_pk_mul_f32 v[48:49], v[48:49], v[50:51]
	v_pk_mul_f32 v[50:51], v[134:135], v[136:137]
	v_pk_mul_f32 v[140:141], v[44:45], v[48:49]
	v_pk_mul_f32 v[142:143], v[46:47], v[50:51]
	v_lshlrev_b32_e32 v46, 16, v132
	v_mul_f32_e32 v46, 0xbfb8aa3b, v46
	v_exp_f32_e32 v46, v46
	v_lshlrev_b32_e32 v47, 16, v144
	v_mul_f32_e32 v47, 0xbfb8aa3b, v47
	v_exp_f32_e32 v47, v47
	v_add_f32_e32 v44, 1.0, v46
	v_and_b32_e32 v46, 0xffff0000, v132
	v_mul_f32_e32 v46, 0xbfb8aa3b, v46
	v_add_f32_e32 v45, 1.0, v47
	v_exp_f32_e32 v47, v46
	v_and_b32_e32 v46, 0xffff0000, v144
	v_mul_f32_e32 v46, 0xbfb8aa3b, v46
	v_exp_f32_e32 v48, v46
	v_lshlrev_b32_e32 v49, 16, v145
	v_mul_f32_e32 v49, 0xbfb8aa3b, v49
	v_and_b32_e32 v51, 0xffff0000, v145
	v_exp_f32_e32 v49, v49
	v_mul_f32_e32 v51, 0xbfb8aa3b, v51
	v_exp_f32_e32 v51, v51
	v_rcp_f32_e32 v46, v45
	v_add_f32_e32 v45, 1.0, v47
	v_add_f32_e32 v47, 1.0, v48
	v_lshlrev_b32_e32 v48, 16, v133
	v_and_b32_e32 v50, 0xffff0000, v133
	v_mul_f32_e32 v48, 0xbfb8aa3b, v48
	v_mul_f32_e32 v50, 0xbfb8aa3b, v50
	v_exp_f32_e32 v48, v48
	v_add_f32_e32 v49, 1.0, v49
	v_exp_f32_e32 v132, v50
	v_rcp_f32_e32 v50, v49
	v_add_f32_e32 v49, 1.0, v51
	v_rcp_f32_e32 v47, v47
	v_rcp_f32_e32 v51, v49
	v_add_f32_e32 v48, 1.0, v48
	v_add_f32_e32 v49, 1.0, v132
	v_min_f32_e32 v44, 0x7149f2ca, v44
	v_min_f32_e32 v45, 0x7149f2ca, v45
	v_min_f32_e32 v48, 0x7149f2ca, v48
	v_min_f32_e32 v49, 0x7149f2ca, v49
	s_waitcnt vmcnt(0)
	v_pk_mul_f32 v[44:45], v[44:45], v[46:47]
	v_pk_mul_f32 v[46:47], v[48:49], v[50:51]
	v_pk_mul_f32 v[148:149], v[40:41], v[44:45]
	v_pk_mul_f32 v[150:151], v[42:43], v[46:47]
	s_barrier

.LBB0_646:
	v_lshl_or_b32 v41, s23, 8, v236
	v_or_b32_e32 v41, s29, v41
	v_mov_b32_e32 v43, 0
	v_lshl_add_u32 v40, s9, 8, v44
	v_lshlrev_b32_e32 v42, 1, v41
	v_mov_b32_e32 v41, v43
	v_lshl_add_u64 v[44:45], s[6:7], 0, v[42:43]
	v_lshlrev_b64 v[46:47], 11, v[40:41]
	v_lshl_add_u64 v[46:47], v[44:45], 0, v[46:47]
	global_load_dwordx4 v[188:191], v[46:47], off nt
	global_load_dwordx4 v[192:195], v[46:47], off offset:256 nt
	v_or_b32_e32 v48, 16, v40
	v_mov_b32_e32 v49, v43
	v_or_b32_e32 v50, 32, v40
	v_mov_b32_e32 v51, v43
	v_or_b32_e32 v132, 48, v40
	v_mov_b32_e32 v133, v43
	v_add_u32_e32 v134, 0x80, v40
	v_mov_b32_e32 v135, v43
	v_add_u32_e32 v136, 0x90, v40
	v_mov_b32_e32 v137, v43
	v_add_u32_e32 v138, 0xa0, v40
	v_mov_b32_e32 v139, v43
	v_add_u32_e32 v144, 0xb0, v40
	v_mov_b32_e32 v145, v43
	v_lshlrev_b64 v[48:49], 11, v[48:49]
	v_lshlrev_b64 v[50:51], 11, v[50:51]
	v_lshlrev_b64 v[132:133], 11, v[132:133]
	v_lshlrev_b64 v[134:135], 11, v[134:135]
	v_lshlrev_b64 v[136:137], 11, v[136:137]
	v_lshlrev_b64 v[138:139], 11, v[138:139]
	v_lshlrev_b64 v[144:145], 11, v[144:145]
	v_lshl_add_u32 v181, v40, 11, v42
	v_lshl_add_u64 v[40:41], v[44:45], 0, v[48:49]
	v_lshl_add_u64 v[42:43], v[44:45], 0, v[50:51]
	v_lshl_add_u64 v[46:47], v[44:45], 0, v[132:133]
	v_lshl_add_u64 v[48:49], v[44:45], 0, v[134:135]
	v_lshl_add_u64 v[50:51], v[44:45], 0, v[136:137]
	v_lshl_add_u64 v[200:201], v[44:45], 0, v[138:139]
	v_lshl_add_u64 v[202:203], v[44:45], 0, v[144:145]
	global_load_dwordx4 v[196:199], v[40:41], off nt
	global_load_dwordx4 v[176:179], v[40:41], off offset:256 nt
	global_load_dwordx4 v[172:175], v[42:43], off nt
	global_load_dwordx4 v[168:171], v[42:43], off offset:256 nt
	global_load_dwordx4 v[164:167], v[46:47], off nt
	global_load_dwordx4 v[160:163], v[46:47], off offset:256 nt
	global_load_dwordx4 v[156:159], v[48:49], off nt
	global_load_dwordx4 v[152:155], v[48:49], off offset:256 nt
	global_load_dwordx4 v[144:147], v[50:51], off nt
	global_load_dwordx4 v[136:139], v[50:51], off offset:256 nt
	global_load_dwordx4 v[132:135], v[200:201], off nt
	s_nop 0
	global_load_dwordx4 v[48:51], v[200:201], off offset:256 nt
	global_load_dwordx4 v[44:47], v[202:203], off nt
	global_load_dwordx4 v[40:43], v[202:203], off offset:256 nt
	s_and_b32 s9, s22, 0xffff
	s_mov_b32 s11, 0x20000
	s_mov_b32 s10, 0x7ffffff0
	s_waitcnt vmcnt(0)
	v_lshlrev_b32_e32 v183, 16, v188
	v_and_b32_e32 v185, 0xffff0000, v188
	v_lshlrev_b32_e32 v188, 16, v190
	v_mul_f32_e32 v183, 0xbfb8aa3b, v183
	v_mul_f32_e32 v188, 0xbfb8aa3b, v188
	v_exp_f32_e32 v183, v183
	v_lshlrev_b32_e32 v187, 16, v189
	v_and_b32_e32 v201, 0xffff0000, v189
	v_and_b32_e32 v189, 0xffff0000, v190
	v_mul_f32_e32 v185, 0xbfb8aa3b, v185
	v_exp_f32_e32 v188, v188
	v_mul_f32_e32 v189, 0xbfb8aa3b, v189
	v_exp_f32_e32 v185, v185
	v_exp_f32_e32 v189, v189
	v_add_f32_e32 v183, 1.0, v183
	v_lshlrev_b32_e32 v190, 16, v191
	v_add_f32_e32 v188, 1.0, v188
	v_min_f32_e32 v183, 0x7149f2ca, v183
	v_and_b32_e32 v203, 0xffff0000, v191
	v_mul_f32_e32 v190, 0xbfb8aa3b, v190
	v_add_f32_e32 v185, 1.0, v185
	v_min_f32_e32 v191, 0x7149f2ca, v188
	v_rcp_f32_e32 v188, v183
	v_mul_f32_e32 v183, 0xbfb8aa3b, v201
	v_exp_f32_e32 v190, v190
	v_add_f32_e32 v189, 1.0, v189
	v_min_f32_e32 v185, 0x7149f2ca, v185
	v_exp_f32_e32 v183, v183
	v_mul_f32_e32 v187, 0xbfb8aa3b, v187
	v_min_f32_e32 v200, 0x7149f2ca, v189
	v_rcp_f32_e32 v189, v185
	v_mul_f32_e32 v185, 0xbfb8aa3b, v203
	v_exp_f32_e32 v187, v187
	v_exp_f32_e32 v185, v185
	v_add_f32_e32 v190, 1.0, v190
	v_add_f32_e32 v183, 1.0, v183
	v_min_f32_e32 v202, 0x7149f2ca, v190
	v_rcp_f32_e32 v190, v191
	v_rcp_f32_e32 v191, v200
	v_min_f32_e32 v183, 0x7149f2ca, v183
	v_add_f32_e32 v187, 1.0, v187
	v_rcp_f32_e32 v201, v183
	v_add_f32_e32 v183, 1.0, v185
	v_min_f32_e32 v187, 0x7149f2ca, v187
	v_min_f32_e32 v183, 0x7149f2ca, v183
	v_rcp_f32_e32 v200, v187
	v_rcp_f32_e32 v202, v202
	v_rcp_f32_e32 v203, v183
	v_pk_mul_f32 v[148:149], v[148:149], v[188:189]
	v_pk_mul_f32 v[188:189], v[140:141], v[190:191]
	v_cvt_pk_bf16_f32 v140, v148, v149
	v_and_b32_e32 v148, 0xffff0000, v194
	v_mul_f32_e32 v148, 0xbfb8aa3b, v148
	v_exp_f32_e32 v148, v148
	v_pk_mul_f32 v[150:151], v[150:151], v[200:201]
	v_pk_mul_f32 v[190:191], v[142:143], v[202:203]
	v_cvt_pk_bf16_f32 v141, v150, v151
	v_cvt_pk_bf16_f32 v142, v188, v189
	v_cvt_pk_bf16_f32 v143, v190, v191
	buffer_store_dwordx4 v[140:143], v181, s[8:11], 0 offen sc1
	v_add_f32_e32 v148, 1.0, v148
	v_and_b32_e32 v149, 0xffff0000, v193
	v_lshlrev_b32_e32 v140, 16, v192
	v_and_b32_e32 v141, 0xffff0000, v192
	v_lshlrev_b32_e32 v143, 16, v193
	v_lshlrev_b32_e32 v142, 16, v194
	v_mul_f32_e32 v140, 0xbfb8aa3b, v140
	v_mul_f32_e32 v141, 0xbfb8aa3b, v141
	v_lshlrev_b32_e32 v150, 16, v195
	v_exp_f32_e32 v140, v140
	v_and_b32_e32 v151, 0xffff0000, v195
	v_mul_f32_e32 v142, 0xbfb8aa3b, v142
	v_exp_f32_e32 v141, v141
	v_min_f32_e32 v148, 0x7149f2ca, v148
	v_mul_f32_e32 v143, 0xbfb8aa3b, v143
	v_exp_f32_e32 v142, v142
	v_exp_f32_e32 v183, v143
	v_rcp_f32_e32 v143, v148
	v_mul_f32_e32 v148, 0xbfb8aa3b, v150
	v_mul_f32_e32 v149, 0xbfb8aa3b, v149
	v_mul_f32_e32 v151, 0xbfb8aa3b, v151
	v_exp_f32_e32 v150, v148
	v_exp_f32_e32 v149, v149
	v_exp_f32_e32 v151, v151
	v_add_f32_e32 v140, 1.0, v140
	v_add_f32_e32 v141, 1.0, v141
	v_min_f32_e32 v140, 0x7149f2ca, v140
	v_add_f32_e32 v142, 1.0, v142
	v_min_f32_e32 v141, 0x7149f2ca, v141
	v_rcp_f32_e32 v140, v140
	v_min_f32_e32 v142, 0x7149f2ca, v142
	v_rcp_f32_e32 v141, v141
	v_add_f32_e32 v148, 1.0, v183
	v_add_f32_e32 v150, 1.0, v150
	v_add_f32_e32 v149, 1.0, v149
	v_add_f32_e32 v151, 1.0, v151
	v_rcp_f32_e32 v142, v142
	v_min_f32_e32 v148, 0x7149f2ca, v148
	v_min_f32_e32 v150, 0x7149f2ca, v150
	v_min_f32_e32 v149, 0x7149f2ca, v149
	v_min_f32_e32 v151, 0x7149f2ca, v151
	v_rcp_f32_e32 v148, v148
	v_rcp_f32_e32 v150, v150
	v_rcp_f32_e32 v149, v149
	v_rcp_f32_e32 v151, v151
	v_pk_mul_f32 v[128:129], v[128:129], v[140:141]
	v_pk_mul_f32 v[140:141], v[56:57], v[142:143]
	v_cvt_pk_bf16_f32 v56, v128, v129
	v_and_b32_e32 v128, 0xffff0000, v198
	v_pk_mul_f32 v[130:131], v[130:131], v[148:149]
	v_pk_mul_f32 v[142:143], v[58:59], v[150:151]
	v_mul_f32_e32 v128, 0xbfb8aa3b, v128
	v_cvt_pk_bf16_f32 v57, v130, v131
	v_cvt_pk_bf16_f32 v58, v140, v141
	v_cvt_pk_bf16_f32 v59, v142, v143
	v_exp_f32_e32 v128, v128
	buffer_store_dwordx4 v[56:59], v181, s[8:11], 0 offen offset:256 sc1
	v_and_b32_e32 v129, 0xffff0000, v197
	v_mul_f32_e32 v129, 0xbfb8aa3b, v129
	v_lshlrev_b32_e32 v56, 16, v196
	v_and_b32_e32 v57, 0xffff0000, v196
	v_lshlrev_b32_e32 v59, 16, v197
	v_mul_f32_e32 v56, 0xbfb8aa3b, v56
	v_mul_f32_e32 v57, 0xbfb8aa3b, v57
	v_mul_f32_e32 v59, 0xbfb8aa3b, v59
	v_exp_f32_e32 v56, v56
	v_exp_f32_e32 v57, v57
	v_exp_f32_e32 v141, v59
	v_exp_f32_e32 v129, v129
	v_add_f32_e32 v128, 1.0, v128
	v_lshlrev_b32_e32 v58, 16, v198
	v_lshlrev_b32_e32 v130, 16, v199
	v_and_b32_e32 v131, 0xffff0000, v199
	v_min_f32_e32 v128, 0x7149f2ca, v128
	v_mul_f32_e32 v58, 0xbfb8aa3b, v58
	v_rcp_f32_e32 v59, v128
	v_mul_f32_e32 v128, 0xbfb8aa3b, v130
	v_mul_f32_e32 v131, 0xbfb8aa3b, v131
	v_exp_f32_e32 v58, v58
	v_add_f32_e32 v56, 1.0, v56
	v_add_f32_e32 v57, 1.0, v57
	v_exp_f32_e32 v130, v128
	v_add_f32_e32 v128, 1.0, v141
	v_exp_f32_e32 v131, v131
	v_add_f32_e32 v129, 1.0, v129
	v_min_f32_e32 v56, 0x7149f2ca, v56
	v_min_f32_e32 v57, 0x7149f2ca, v57
	v_min_f32_e32 v128, 0x7149f2ca, v128
	v_min_f32_e32 v129, 0x7149f2ca, v129
	v_rcp_f32_e32 v56, v56
	v_rcp_f32_e32 v57, v57
	v_rcp_f32_e32 v128, v128
	v_rcp_f32_e32 v129, v129
	v_add_f32_e32 v58, 1.0, v58
	v_add_f32_e32 v130, 1.0, v130
	v_add_f32_e32 v131, 1.0, v131
	v_min_f32_e32 v58, 0x7149f2ca, v58
	v_min_f32_e32 v130, 0x7149f2ca, v130
	v_min_f32_e32 v131, 0x7149f2ca, v131
	v_rcp_f32_e32 v58, v58
	v_rcp_f32_e32 v130, v130
	v_rcp_f32_e32 v131, v131
	v_pk_mul_f32 v[56:57], v[64:65], v[56:57]
	v_pk_mul_f32 v[64:65], v[66:67], v[128:129]
	v_cvt_pk_bf16_f32 v56, v56, v57
	v_cvt_pk_bf16_f32 v57, v64, v65
	v_and_b32_e32 v64, 0xffff0000, v178
	v_mul_f32_e32 v64, 0xbfb8aa3b, v64
	v_exp_f32_e32 v64, v64
	v_pk_mul_f32 v[58:59], v[68:69], v[58:59]
	v_pk_mul_f32 v[66:67], v[70:71], v[130:131]
	v_add_u32_e32 v140, 0x8000, v181
	v_cvt_pk_bf16_f32 v58, v58, v59
	v_cvt_pk_bf16_f32 v59, v66, v67
	buffer_store_dwordx4 v[56:59], v140, s[8:11], 0 offen sc1
	v_and_b32_e32 v65, 0xffff0000, v177
	v_add_f32_e32 v64, 1.0, v64
	v_lshlrev_b32_e32 v56, 16, v176
	v_and_b32_e32 v57, 0xffff0000, v176
	v_lshlrev_b32_e32 v59, 16, v177
	v_mul_f32_e32 v56, 0xbfb8aa3b, v56
	v_mul_f32_e32 v57, 0xbfb8aa3b, v57
	v_mul_f32_e32 v59, 0xbfb8aa3b, v59
	v_mul_f32_e32 v65, 0xbfb8aa3b, v65
	v_lshlrev_b32_e32 v58, 16, v178
	v_lshlrev_b32_e32 v66, 16, v179
	v_exp_f32_e32 v56, v56
	v_and_b32_e32 v67, 0xffff0000, v179
	v_exp_f32_e32 v57, v57
	v_min_f32_e32 v64, 0x7149f2ca, v64
	v_exp_f32_e32 v68, v59
	v_exp_f32_e32 v65, v65
	v_mul_f32_e32 v58, 0xbfb8aa3b, v58
	v_rcp_f32_e32 v59, v64
	v_mul_f32_e32 v64, 0xbfb8aa3b, v66
	v_mul_f32_e32 v67, 0xbfb8aa3b, v67
	v_exp_f32_e32 v58, v58
	v_exp_f32_e32 v66, v64
	v_exp_f32_e32 v67, v67
	v_add_f32_e32 v56, 1.0, v56
	v_add_f32_e32 v57, 1.0, v57
	v_add_f32_e32 v64, 1.0, v68
	v_add_f32_e32 v65, 1.0, v65
	v_min_f32_e32 v56, 0x7149f2ca, v56
	v_min_f32_e32 v57, 0x7149f2ca, v57
	v_min_f32_e32 v64, 0x7149f2ca, v64
	v_min_f32_e32 v65, 0x7149f2ca, v65
	v_rcp_f32_e32 v56, v56
	v_add_f32_e32 v58, 1.0, v58
	v_rcp_f32_e32 v57, v57
	v_rcp_f32_e32 v64, v64
	v_add_f32_e32 v66, 1.0, v66
	v_rcp_f32_e32 v65, v65
	v_add_f32_e32 v67, 1.0, v67
	v_min_f32_e32 v58, 0x7149f2ca, v58
	v_min_f32_e32 v66, 0x7149f2ca, v66
	v_min_f32_e32 v67, 0x7149f2ca, v67
	v_rcp_f32_e32 v58, v58
	v_rcp_f32_e32 v66, v66
	v_rcp_f32_e32 v67, v67
	v_pk_mul_f32 v[56:57], v[80:81], v[56:57]
	v_pk_mul_f32 v[64:65], v[82:83], v[64:65]
	v_cvt_pk_bf16_f32 v56, v56, v57
	v_cvt_pk_bf16_f32 v57, v64, v65
	v_and_b32_e32 v64, 0xffff0000, v174
	v_pk_mul_f32 v[58:59], v[84:85], v[58:59]
	v_pk_mul_f32 v[66:67], v[86:87], v[66:67]
	v_mul_f32_e32 v64, 0xbfb8aa3b, v64
	v_cvt_pk_bf16_f32 v58, v58, v59
	v_cvt_pk_bf16_f32 v59, v66, v67
	v_exp_f32_e32 v64, v64
	buffer_store_dwordx4 v[56:59], v140, s[8:11], 0 offen offset:256 sc1
	v_and_b32_e32 v65, 0xffff0000, v173
	v_mul_f32_e32 v65, 0xbfb8aa3b, v65
	v_lshlrev_b32_e32 v56, 16, v172
	v_and_b32_e32 v57, 0xffff0000, v172
	v_lshlrev_b32_e32 v59, 16, v173
	v_mul_f32_e32 v56, 0xbfb8aa3b, v56
	v_mul_f32_e32 v57, 0xbfb8aa3b, v57
	v_mul_f32_e32 v59, 0xbfb8aa3b, v59
	v_exp_f32_e32 v56, v56
	v_exp_f32_e32 v57, v57
	v_exp_f32_e32 v69, v59
	v_exp_f32_e32 v65, v65
	v_add_f32_e32 v64, 1.0, v64
	v_lshlrev_b32_e32 v58, 16, v174
	v_lshlrev_b32_e32 v66, 16, v175
	v_and_b32_e32 v67, 0xffff0000, v175
	v_min_f32_e32 v64, 0x7149f2ca, v64
	v_mul_f32_e32 v58, 0xbfb8aa3b, v58
	v_rcp_f32_e32 v59, v64
	v_mul_f32_e32 v64, 0xbfb8aa3b, v66
	v_mul_f32_e32 v67, 0xbfb8aa3b, v67
	v_exp_f32_e32 v58, v58
	v_add_f32_e32 v56, 1.0, v56
	v_add_f32_e32 v57, 1.0, v57
	v_exp_f32_e32 v66, v64
	v_add_f32_e32 v64, 1.0, v69
	v_exp_f32_e32 v67, v67
	v_add_f32_e32 v65, 1.0, v65
	v_min_f32_e32 v56, 0x7149f2ca, v56
	v_min_f32_e32 v57, 0x7149f2ca, v57
	v_min_f32_e32 v64, 0x7149f2ca, v64
	v_min_f32_e32 v65, 0x7149f2ca, v65
	v_rcp_f32_e32 v56, v56
	v_rcp_f32_e32 v57, v57
	v_rcp_f32_e32 v64, v64
	v_rcp_f32_e32 v65, v65
	v_add_f32_e32 v58, 1.0, v58
	v_add_f32_e32 v66, 1.0, v66
	v_add_f32_e32 v67, 1.0, v67
	v_min_f32_e32 v58, 0x7149f2ca, v58
	v_min_f32_e32 v66, 0x7149f2ca, v66
	v_min_f32_e32 v67, 0x7149f2ca, v67
	v_rcp_f32_e32 v58, v58
	v_rcp_f32_e32 v66, v66
	v_rcp_f32_e32 v67, v67
	v_pk_mul_f32 v[56:57], v[88:89], v[56:57]
	v_pk_mul_f32 v[64:65], v[90:91], v[64:65]
	v_cvt_pk_bf16_f32 v56, v56, v57
	v_cvt_pk_bf16_f32 v57, v64, v65
	v_and_b32_e32 v64, 0xffff0000, v170
	v_mul_f32_e32 v64, 0xbfb8aa3b, v64
	v_exp_f32_e32 v64, v64
	v_pk_mul_f32 v[58:59], v[96:97], v[58:59]
	v_pk_mul_f32 v[66:67], v[98:99], v[66:67]
	v_add_u32_e32 v68, 0x10000, v181
	v_cvt_pk_bf16_f32 v58, v58, v59
	v_cvt_pk_bf16_f32 v59, v66, v67
	buffer_store_dwordx4 v[56:59], v68, s[8:11], 0 offen sc1
	v_and_b32_e32 v65, 0xffff0000, v169
	v_add_f32_e32 v64, 1.0, v64
	v_lshlrev_b32_e32 v56, 16, v168
	v_and_b32_e32 v57, 0xffff0000, v168
	v_lshlrev_b32_e32 v59, 16, v169
	v_mul_f32_e32 v56, 0xbfb8aa3b, v56
	v_mul_f32_e32 v57, 0xbfb8aa3b, v57
	v_mul_f32_e32 v59, 0xbfb8aa3b, v59
	v_mul_f32_e32 v65, 0xbfb8aa3b, v65
	v_lshlrev_b32_e32 v58, 16, v170
	v_lshlrev_b32_e32 v66, 16, v171
	v_exp_f32_e32 v56, v56
	v_and_b32_e32 v67, 0xffff0000, v171
	v_exp_f32_e32 v57, v57
	v_min_f32_e32 v64, 0x7149f2ca, v64
	v_exp_f32_e32 v69, v59
	v_exp_f32_e32 v65, v65
	v_mul_f32_e32 v58, 0xbfb8aa3b, v58
	v_rcp_f32_e32 v59, v64
	v_mul_f32_e32 v64, 0xbfb8aa3b, v66
	v_mul_f32_e32 v67, 0xbfb8aa3b, v67
	v_exp_f32_e32 v58, v58
	v_exp_f32_e32 v66, v64
	v_exp_f32_e32 v67, v67
	v_add_f32_e32 v56, 1.0, v56
	v_add_f32_e32 v57, 1.0, v57
	v_add_f32_e32 v64, 1.0, v69
	v_add_f32_e32 v65, 1.0, v65
	v_min_f32_e32 v56, 0x7149f2ca, v56
	v_min_f32_e32 v57, 0x7149f2ca, v57
	v_min_f32_e32 v64, 0x7149f2ca, v64
	v_min_f32_e32 v65, 0x7149f2ca, v65
	v_rcp_f32_e32 v56, v56
	v_add_f32_e32 v58, 1.0, v58
	v_rcp_f32_e32 v57, v57
	v_rcp_f32_e32 v64, v64
	v_add_f32_e32 v66, 1.0, v66
	v_rcp_f32_e32 v65, v65
	v_add_f32_e32 v67, 1.0, v67
	v_min_f32_e32 v58, 0x7149f2ca, v58
	v_min_f32_e32 v66, 0x7149f2ca, v66
	v_min_f32_e32 v67, 0x7149f2ca, v67
	v_rcp_f32_e32 v58, v58
	v_rcp_f32_e32 v66, v66
	v_rcp_f32_e32 v67, v67
	v_pk_mul_f32 v[56:57], v[104:105], v[56:57]
	v_pk_mul_f32 v[64:65], v[106:107], v[64:65]
	v_cvt_pk_bf16_f32 v56, v56, v57
	v_cvt_pk_bf16_f32 v57, v64, v65
	v_and_b32_e32 v64, 0xffff0000, v166
	v_pk_mul_f32 v[58:59], v[108:109], v[58:59]
	v_pk_mul_f32 v[66:67], v[110:111], v[66:67]
	v_mul_f32_e32 v64, 0xbfb8aa3b, v64
	v_cvt_pk_bf16_f32 v58, v58, v59
	v_cvt_pk_bf16_f32 v59, v66, v67
	v_exp_f32_e32 v64, v64
	buffer_store_dwordx4 v[56:59], v68, s[8:11], 0 offen offset:256 sc1
	v_and_b32_e32 v65, 0xffff0000, v165
	v_mul_f32_e32 v65, 0xbfb8aa3b, v65
	v_lshlrev_b32_e32 v56, 16, v164
	v_and_b32_e32 v57, 0xffff0000, v164
	v_lshlrev_b32_e32 v59, 16, v165
	v_mul_f32_e32 v56, 0xbfb8aa3b, v56
	v_mul_f32_e32 v57, 0xbfb8aa3b, v57
	v_mul_f32_e32 v59, 0xbfb8aa3b, v59
	v_exp_f32_e32 v56, v56
	v_exp_f32_e32 v57, v57
	v_exp_f32_e32 v69, v59
	v_exp_f32_e32 v65, v65
	v_add_f32_e32 v64, 1.0, v64
	v_lshlrev_b32_e32 v58, 16, v166
	v_lshlrev_b32_e32 v66, 16, v167
	v_and_b32_e32 v67, 0xffff0000, v167
	v_min_f32_e32 v64, 0x7149f2ca, v64
	v_mul_f32_e32 v58, 0xbfb8aa3b, v58
	v_rcp_f32_e32 v59, v64
	v_mul_f32_e32 v64, 0xbfb8aa3b, v66
	v_mul_f32_e32 v67, 0xbfb8aa3b, v67
	v_exp_f32_e32 v58, v58
	v_add_f32_e32 v56, 1.0, v56
	v_add_f32_e32 v57, 1.0, v57
	v_exp_f32_e32 v66, v64
	v_add_f32_e32 v64, 1.0, v69
	v_exp_f32_e32 v67, v67
	v_add_f32_e32 v65, 1.0, v65
	v_min_f32_e32 v56, 0x7149f2ca, v56
	v_min_f32_e32 v57, 0x7149f2ca, v57
	v_min_f32_e32 v64, 0x7149f2ca, v64
	v_min_f32_e32 v65, 0x7149f2ca, v65
	v_rcp_f32_e32 v56, v56
	v_rcp_f32_e32 v57, v57
	v_rcp_f32_e32 v64, v64
	v_rcp_f32_e32 v65, v65
	v_add_f32_e32 v58, 1.0, v58
	v_add_f32_e32 v66, 1.0, v66
	v_add_f32_e32 v67, 1.0, v67
	v_min_f32_e32 v58, 0x7149f2ca, v58
	v_min_f32_e32 v66, 0x7149f2ca, v66
	v_min_f32_e32 v67, 0x7149f2ca, v67
	v_rcp_f32_e32 v58, v58
	v_rcp_f32_e32 v66, v66
	v_rcp_f32_e32 v67, v67
	v_pk_mul_f32 v[56:57], v[120:121], v[56:57]
	v_pk_mul_f32 v[64:65], v[122:123], v[64:65]
	v_cvt_pk_bf16_f32 v56, v56, v57
	v_cvt_pk_bf16_f32 v57, v64, v65
	v_and_b32_e32 v64, 0xffff0000, v162
	v_mul_f32_e32 v64, 0xbfb8aa3b, v64
	v_exp_f32_e32 v64, v64
	v_pk_mul_f32 v[58:59], v[124:125], v[58:59]
	v_pk_mul_f32 v[66:67], v[126:127], v[66:67]
	v_add_u32_e32 v68, 0x18000, v181
	v_cvt_pk_bf16_f32 v58, v58, v59
	v_cvt_pk_bf16_f32 v59, v66, v67
	buffer_store_dwordx4 v[56:59], v68, s[8:11], 0 offen sc1
	v_and_b32_e32 v65, 0xffff0000, v161
	v_add_f32_e32 v64, 1.0, v64
	v_lshlrev_b32_e32 v56, 16, v160
	v_and_b32_e32 v57, 0xffff0000, v160
	v_lshlrev_b32_e32 v59, 16, v161
	v_mul_f32_e32 v56, 0xbfb8aa3b, v56
	v_mul_f32_e32 v57, 0xbfb8aa3b, v57
	v_mul_f32_e32 v59, 0xbfb8aa3b, v59
	v_mul_f32_e32 v65, 0xbfb8aa3b, v65
	v_lshlrev_b32_e32 v58, 16, v162
	v_lshlrev_b32_e32 v66, 16, v163
	v_exp_f32_e32 v56, v56
	v_and_b32_e32 v67, 0xffff0000, v163
	v_exp_f32_e32 v57, v57
	v_min_f32_e32 v64, 0x7149f2ca, v64
	v_exp_f32_e32 v69, v59
	v_exp_f32_e32 v65, v65
	v_mul_f32_e32 v58, 0xbfb8aa3b, v58
	v_rcp_f32_e32 v59, v64
	v_mul_f32_e32 v64, 0xbfb8aa3b, v66
	v_mul_f32_e32 v67, 0xbfb8aa3b, v67
	v_exp_f32_e32 v58, v58
	v_exp_f32_e32 v66, v64
	v_exp_f32_e32 v67, v67
	v_add_f32_e32 v56, 1.0, v56
	v_add_f32_e32 v57, 1.0, v57
	v_add_f32_e32 v64, 1.0, v69
	v_add_f32_e32 v65, 1.0, v65
	v_min_f32_e32 v56, 0x7149f2ca, v56
	v_min_f32_e32 v57, 0x7149f2ca, v57
	v_min_f32_e32 v64, 0x7149f2ca, v64
	v_min_f32_e32 v65, 0x7149f2ca, v65
	v_rcp_f32_e32 v56, v56
	v_add_f32_e32 v58, 1.0, v58
	v_rcp_f32_e32 v57, v57
	v_rcp_f32_e32 v64, v64
	v_add_f32_e32 v66, 1.0, v66
	v_rcp_f32_e32 v65, v65
	v_add_f32_e32 v67, 1.0, v67
	v_min_f32_e32 v58, 0x7149f2ca, v58
	v_min_f32_e32 v66, 0x7149f2ca, v66
	v_min_f32_e32 v67, 0x7149f2ca, v67
	v_rcp_f32_e32 v58, v58
	v_rcp_f32_e32 v66, v66
	v_rcp_f32_e32 v67, v67
	v_pk_mul_f32 v[56:57], v[116:117], v[56:57]
	v_pk_mul_f32 v[64:65], v[118:119], v[64:65]
	v_cvt_pk_bf16_f32 v56, v56, v57
	v_cvt_pk_bf16_f32 v57, v64, v65
	v_and_b32_e32 v64, 0xffff0000, v158
	v_pk_mul_f32 v[58:59], v[112:113], v[58:59]
	v_pk_mul_f32 v[66:67], v[114:115], v[66:67]
	v_mul_f32_e32 v64, 0xbfb8aa3b, v64
	v_cvt_pk_bf16_f32 v58, v58, v59
	v_cvt_pk_bf16_f32 v59, v66, v67
	v_exp_f32_e32 v64, v64
	buffer_store_dwordx4 v[56:59], v68, s[8:11], 0 offen offset:256 sc1
	v_and_b32_e32 v65, 0xffff0000, v157
	v_mul_f32_e32 v65, 0xbfb8aa3b, v65
	v_lshlrev_b32_e32 v56, 16, v156
	v_and_b32_e32 v57, 0xffff0000, v156
	v_lshlrev_b32_e32 v59, 16, v157
	v_mul_f32_e32 v56, 0xbfb8aa3b, v56
	v_mul_f32_e32 v57, 0xbfb8aa3b, v57
	v_mul_f32_e32 v59, 0xbfb8aa3b, v59
	v_exp_f32_e32 v56, v56
	v_exp_f32_e32 v57, v57
	v_exp_f32_e32 v69, v59
	v_exp_f32_e32 v65, v65
	v_add_f32_e32 v64, 1.0, v64
	v_lshlrev_b32_e32 v66, 16, v159
	v_min_f32_e32 v64, 0x7149f2ca, v64
	v_lshlrev_b32_e32 v58, 16, v158
	v_and_b32_e32 v67, 0xffff0000, v159
	v_rcp_f32_e32 v59, v64
	v_mul_f32_e32 v64, 0xbfb8aa3b, v66
	v_mul_f32_e32 v58, 0xbfb8aa3b, v58
	v_add_f32_e32 v56, 1.0, v56
	v_add_f32_e32 v57, 1.0, v57
	v_exp_f32_e32 v66, v64
	v_add_f32_e32 v64, 1.0, v69
	v_mul_f32_e32 v67, 0xbfb8aa3b, v67
	v_add_f32_e32 v65, 1.0, v65
	v_exp_f32_e32 v58, v58
	v_min_f32_e32 v56, 0x7149f2ca, v56
	v_min_f32_e32 v57, 0x7149f2ca, v57
	v_min_f32_e32 v64, 0x7149f2ca, v64
	v_exp_f32_e32 v67, v67
	v_min_f32_e32 v65, 0x7149f2ca, v65
	v_rcp_f32_e32 v56, v56
	v_rcp_f32_e32 v57, v57
	v_rcp_f32_e32 v64, v64
	v_rcp_f32_e32 v65, v65
	v_add_f32_e32 v58, 1.0, v58
	v_add_f32_e32 v66, 1.0, v66
	v_add_f32_e32 v67, 1.0, v67
	v_min_f32_e32 v58, 0x7149f2ca, v58
	v_min_f32_e32 v66, 0x7149f2ca, v66
	v_min_f32_e32 v67, 0x7149f2ca, v67
	v_pk_mul_f32 v[56:57], v[100:101], v[56:57]
	v_pk_mul_f32 v[64:65], v[102:103], v[64:65]
	v_rcp_f32_e32 v58, v58
	v_rcp_f32_e32 v66, v66
	v_rcp_f32_e32 v67, v67
	v_cvt_pk_bf16_f32 v56, v56, v57
	v_cvt_pk_bf16_f32 v57, v64, v65
	v_and_b32_e32 v64, 0xffff0000, v154
	v_mul_f32_e32 v64, 0xbfb8aa3b, v64
	v_exp_f32_e32 v64, v64
	v_pk_mul_f32 v[58:59], v[92:93], v[58:59]
	v_pk_mul_f32 v[66:67], v[94:95], v[66:67]
	v_add_u32_e32 v68, 0x40000, v181
	v_cvt_pk_bf16_f32 v58, v58, v59
	v_cvt_pk_bf16_f32 v59, v66, v67
	buffer_store_dwordx4 v[56:59], v68, s[8:11], 0 offen sc1
	v_and_b32_e32 v65, 0xffff0000, v153
	v_add_f32_e32 v64, 1.0, v64
	v_lshlrev_b32_e32 v56, 16, v152
	v_and_b32_e32 v57, 0xffff0000, v152
	v_lshlrev_b32_e32 v59, 16, v153
	v_lshlrev_b32_e32 v58, 16, v154
	v_lshlrev_b32_e32 v66, 16, v155
	v_mul_f32_e32 v56, 0xbfb8aa3b, v56
	v_and_b32_e32 v67, 0xffff0000, v155
	v_mul_f32_e32 v57, 0xbfb8aa3b, v57
	v_min_f32_e32 v64, 0x7149f2ca, v64
	v_mul_f32_e32 v59, 0xbfb8aa3b, v59
	v_mul_f32_e32 v65, 0xbfb8aa3b, v65
	v_exp_f32_e32 v56, v56
	v_mul_f32_e32 v58, 0xbfb8aa3b, v58
	v_exp_f32_e32 v57, v57
	v_exp_f32_e32 v69, v59
	v_rcp_f32_e32 v59, v64
	v_mul_f32_e32 v64, 0xbfb8aa3b, v66
	v_exp_f32_e32 v65, v65
	v_mul_f32_e32 v67, 0xbfb8aa3b, v67
	v_exp_f32_e32 v58, v58
	v_exp_f32_e32 v66, v64
	v_exp_f32_e32 v67, v67
	v_add_f32_e32 v56, 1.0, v56
	v_add_f32_e32 v57, 1.0, v57
	v_add_f32_e32 v64, 1.0, v69
	v_add_f32_e32 v65, 1.0, v65
	v_min_f32_e32 v56, 0x7149f2ca, v56
	v_add_f32_e32 v58, 1.0, v58
	v_min_f32_e32 v57, 0x7149f2ca, v57
	v_min_f32_e32 v64, 0x7149f2ca, v64
	v_add_f32_e32 v66, 1.0, v66
	v_min_f32_e32 v65, 0x7149f2ca, v65
	v_add_f32_e32 v67, 1.0, v67
	v_rcp_f32_e32 v56, v56
	v_min_f32_e32 v58, 0x7149f2ca, v58
	v_rcp_f32_e32 v57, v57
	v_rcp_f32_e32 v64, v64
	v_min_f32_e32 v66, 0x7149f2ca, v66
	v_rcp_f32_e32 v65, v65
	v_min_f32_e32 v67, 0x7149f2ca, v67
	v_rcp_f32_e32 v58, v58
	v_rcp_f32_e32 v66, v66
	v_rcp_f32_e32 v67, v67
	v_pk_mul_f32 v[56:57], v[76:77], v[56:57]
	v_pk_mul_f32 v[64:65], v[78:79], v[64:65]
	v_pk_mul_f32 v[58:59], v[72:73], v[58:59]
	v_pk_mul_f32 v[66:67], v[74:75], v[66:67]
	v_cvt_pk_bf16_f32 v56, v56, v57
	v_cvt_pk_bf16_f32 v57, v64, v65
	v_and_b32_e32 v64, 0xffff0000, v146
	v_cvt_pk_bf16_f32 v58, v58, v59
	v_cvt_pk_bf16_f32 v59, v66, v67
	v_mul_f32_e32 v64, 0xbfb8aa3b, v64
	buffer_store_dwordx4 v[56:59], v68, s[8:11], 0 offen offset:256 sc1
	v_exp_f32_e32 v64, v64
	v_and_b32_e32 v65, 0xffff0000, v145
	v_lshlrev_b32_e32 v56, 16, v144
	v_and_b32_e32 v57, 0xffff0000, v144
	v_lshlrev_b32_e32 v58, 16, v146
	v_mul_f32_e32 v56, 0xbfb8aa3b, v56
	v_mul_f32_e32 v57, 0xbfb8aa3b, v57
	v_exp_f32_e32 v56, v56
	v_mul_f32_e32 v58, 0xbfb8aa3b, v58
	v_exp_f32_e32 v57, v57
	v_exp_f32_e32 v58, v58
	v_lshlrev_b32_e32 v59, 16, v145
	v_add_f32_e32 v64, 1.0, v64
	v_lshlrev_b32_e32 v66, 16, v147
	v_and_b32_e32 v67, 0xffff0000, v147
	v_min_f32_e32 v64, 0x7149f2ca, v64
	v_mul_f32_e32 v59, 0xbfb8aa3b, v59
	v_add_f32_e32 v56, 1.0, v56
	v_add_f32_e32 v57, 1.0, v57
	v_exp_f32_e32 v69, v59
	v_rcp_f32_e32 v59, v64
	v_mul_f32_e32 v64, 0xbfb8aa3b, v66
	v_mul_f32_e32 v65, 0xbfb8aa3b, v65
	v_mul_f32_e32 v67, 0xbfb8aa3b, v67
	v_min_f32_e32 v56, 0x7149f2ca, v56
	v_add_f32_e32 v58, 1.0, v58
	v_min_f32_e32 v57, 0x7149f2ca, v57
	v_exp_f32_e32 v66, v64
	v_exp_f32_e32 v65, v65
	v_exp_f32_e32 v67, v67
	v_rcp_f32_e32 v56, v56
	v_min_f32_e32 v58, 0x7149f2ca, v58
	v_rcp_f32_e32 v57, v57
	v_rcp_f32_e32 v58, v58
	v_add_f32_e32 v64, 1.0, v69
	v_add_f32_e32 v66, 1.0, v66
	v_add_f32_e32 v65, 1.0, v65
	v_add_f32_e32 v67, 1.0, v67
	v_min_f32_e32 v64, 0x7149f2ca, v64
	v_min_f32_e32 v66, 0x7149f2ca, v66
	v_min_f32_e32 v65, 0x7149f2ca, v65
	v_min_f32_e32 v67, 0x7149f2ca, v67
	v_pk_mul_f32 v[56:57], v[60:61], v[56:57]
	v_rcp_f32_e32 v64, v64
	v_rcp_f32_e32 v66, v66
	v_rcp_f32_e32 v65, v65
	v_rcp_f32_e32 v67, v67
	v_pk_mul_f32 v[58:59], v[52:53], v[58:59]
	v_cvt_pk_bf16_f32 v52, v56, v57
	v_and_b32_e32 v56, 0xffff0000, v138
	v_mul_f32_e32 v56, 0xbfb8aa3b, v56
	v_exp_f32_e32 v56, v56
	v_pk_mul_f32 v[60:61], v[62:63], v[64:65]
	v_pk_mul_f32 v[62:63], v[54:55], v[66:67]
	v_add_u32_e32 v68, 0x48000, v181
	v_cvt_pk_bf16_f32 v53, v60, v61
	v_cvt_pk_bf16_f32 v54, v58, v59
	v_cvt_pk_bf16_f32 v55, v62, v63
	buffer_store_dwordx4 v[52:55], v68, s[8:11], 0 offen sc1
	v_add_f32_e32 v56, 1.0, v56
	v_and_b32_e32 v57, 0xffff0000, v137
	v_lshlrev_b32_e32 v52, 16, v136
	v_and_b32_e32 v53, 0xffff0000, v136
	v_lshlrev_b32_e32 v55, 16, v137
	v_lshlrev_b32_e32 v54, 16, v138
	v_lshlrev_b32_e32 v58, 16, v139
	v_mul_f32_e32 v52, 0xbfb8aa3b, v52
	v_and_b32_e32 v59, 0xffff0000, v139
	v_mul_f32_e32 v53, 0xbfb8aa3b, v53
	v_min_f32_e32 v56, 0x7149f2ca, v56
	v_mul_f32_e32 v55, 0xbfb8aa3b, v55
	v_exp_f32_e32 v52, v52
	v_mul_f32_e32 v54, 0xbfb8aa3b, v54
	v_exp_f32_e32 v53, v53
	v_exp_f32_e32 v60, v55
	v_rcp_f32_e32 v55, v56
	v_mul_f32_e32 v56, 0xbfb8aa3b, v58
	v_mul_f32_e32 v57, 0xbfb8aa3b, v57
	v_mul_f32_e32 v59, 0xbfb8aa3b, v59
	v_exp_f32_e32 v54, v54
	v_exp_f32_e32 v58, v56
	v_exp_f32_e32 v57, v57
	v_exp_f32_e32 v59, v59
	v_add_f32_e32 v52, 1.0, v52
	v_add_f32_e32 v53, 1.0, v53
	v_min_f32_e32 v52, 0x7149f2ca, v52
	v_add_f32_e32 v54, 1.0, v54
	v_min_f32_e32 v53, 0x7149f2ca, v53
	v_add_f32_e32 v56, 1.0, v60
	v_add_f32_e32 v58, 1.0, v58
	v_add_f32_e32 v57, 1.0, v57
	v_add_f32_e32 v59, 1.0, v59
	v_rcp_f32_e32 v52, v52
	v_min_f32_e32 v54, 0x7149f2ca, v54
	v_rcp_f32_e32 v53, v53
	v_min_f32_e32 v56, 0x7149f2ca, v56
	v_min_f32_e32 v58, 0x7149f2ca, v58
	v_min_f32_e32 v57, 0x7149f2ca, v57
	v_min_f32_e32 v59, 0x7149f2ca, v59
	v_rcp_f32_e32 v54, v54
	v_rcp_f32_e32 v56, v56
	v_rcp_f32_e32 v58, v58
	v_rcp_f32_e32 v57, v57
	v_rcp_f32_e32 v59, v59
	v_pk_mul_f32 v[36:37], v[36:37], v[52:53]
	v_pk_mul_f32 v[52:53], v[32:33], v[54:55]
	v_pk_mul_f32 v[38:39], v[38:39], v[56:57]
	v_pk_mul_f32 v[54:55], v[34:35], v[58:59]
	v_cvt_pk_bf16_f32 v32, v36, v37
	v_and_b32_e32 v36, 0xffff0000, v134
	v_cvt_pk_bf16_f32 v33, v38, v39
	v_cvt_pk_bf16_f32 v34, v52, v53
	v_cvt_pk_bf16_f32 v35, v54, v55
	v_mul_f32_e32 v36, 0xbfb8aa3b, v36
	buffer_store_dwordx4 v[32:35], v68, s[8:11], 0 offen offset:256 sc1
	v_exp_f32_e32 v36, v36
	v_and_b32_e32 v37, 0xffff0000, v133
	v_lshlrev_b32_e32 v32, 16, v132
	v_and_b32_e32 v33, 0xffff0000, v132
	v_lshlrev_b32_e32 v34, 16, v134
	v_mul_f32_e32 v32, 0xbfb8aa3b, v32
	v_mul_f32_e32 v33, 0xbfb8aa3b, v33
	v_exp_f32_e32 v32, v32
	v_mul_f32_e32 v34, 0xbfb8aa3b, v34
	v_exp_f32_e32 v33, v33
	v_exp_f32_e32 v34, v34
	v_lshlrev_b32_e32 v35, 16, v133
	v_add_f32_e32 v36, 1.0, v36
	v_lshlrev_b32_e32 v38, 16, v135
	v_and_b32_e32 v39, 0xffff0000, v135
	v_min_f32_e32 v36, 0x7149f2ca, v36
	v_mul_f32_e32 v35, 0xbfb8aa3b, v35
	v_add_f32_e32 v32, 1.0, v32
	v_add_f32_e32 v33, 1.0, v33
	v_exp_f32_e32 v53, v35
	v_rcp_f32_e32 v35, v36
	v_mul_f32_e32 v36, 0xbfb8aa3b, v38
	v_mul_f32_e32 v37, 0xbfb8aa3b, v37
	v_mul_f32_e32 v39, 0xbfb8aa3b, v39
	v_min_f32_e32 v32, 0x7149f2ca, v32
	v_add_f32_e32 v34, 1.0, v34
	v_min_f32_e32 v33, 0x7149f2ca, v33
	v_exp_f32_e32 v38, v36
	v_exp_f32_e32 v37, v37
	v_exp_f32_e32 v39, v39
	v_rcp_f32_e32 v32, v32
	v_min_f32_e32 v34, 0x7149f2ca, v34
	v_rcp_f32_e32 v33, v33
	v_rcp_f32_e32 v34, v34
	v_add_f32_e32 v36, 1.0, v53
	v_add_f32_e32 v38, 1.0, v38
	v_add_f32_e32 v37, 1.0, v37
	v_add_f32_e32 v39, 1.0, v39
	v_min_f32_e32 v36, 0x7149f2ca, v36
	v_min_f32_e32 v38, 0x7149f2ca, v38
	v_min_f32_e32 v37, 0x7149f2ca, v37
	v_min_f32_e32 v39, 0x7149f2ca, v39
	v_pk_mul_f32 v[28:29], v[28:29], v[32:33]
	v_rcp_f32_e32 v36, v36
	v_rcp_f32_e32 v38, v38
	v_rcp_f32_e32 v37, v37
	v_rcp_f32_e32 v39, v39
	v_pk_mul_f32 v[32:33], v[24:25], v[34:35]
	v_cvt_pk_bf16_f32 v24, v28, v29
	v_and_b32_e32 v28, 0xffff0000, v50
	v_mul_f32_e32 v28, 0xbfb8aa3b, v28
	v_exp_f32_e32 v28, v28
	v_pk_mul_f32 v[30:31], v[30:31], v[36:37]
	v_pk_mul_f32 v[34:35], v[26:27], v[38:39]
	v_add_u32_e32 v52, 0x50000, v181
	v_cvt_pk_bf16_f32 v25, v30, v31
	v_cvt_pk_bf16_f32 v26, v32, v33
	v_cvt_pk_bf16_f32 v27, v34, v35
	buffer_store_dwordx4 v[24:27], v52, s[8:11], 0 offen sc1
	v_add_f32_e32 v28, 1.0, v28
	v_and_b32_e32 v29, 0xffff0000, v49
	v_lshlrev_b32_e32 v24, 16, v48
	v_and_b32_e32 v25, 0xffff0000, v48
	v_lshlrev_b32_e32 v27, 16, v49
	v_lshlrev_b32_e32 v26, 16, v50
	v_lshlrev_b32_e32 v30, 16, v51
	v_mul_f32_e32 v24, 0xbfb8aa3b, v24
	v_and_b32_e32 v31, 0xffff0000, v51
	v_mul_f32_e32 v25, 0xbfb8aa3b, v25
	v_min_f32_e32 v28, 0x7149f2ca, v28
	v_mul_f32_e32 v27, 0xbfb8aa3b, v27
	v_exp_f32_e32 v24, v24
	v_mul_f32_e32 v26, 0xbfb8aa3b, v26
	v_exp_f32_e32 v25, v25
	v_exp_f32_e32 v32, v27
	v_rcp_f32_e32 v27, v28
	v_mul_f32_e32 v28, 0xbfb8aa3b, v30
	v_mul_f32_e32 v29, 0xbfb8aa3b, v29
	v_mul_f32_e32 v31, 0xbfb8aa3b, v31
	v_exp_f32_e32 v26, v26
	v_exp_f32_e32 v30, v28
	v_exp_f32_e32 v29, v29
	v_exp_f32_e32 v31, v31
	v_add_f32_e32 v24, 1.0, v24
	v_add_f32_e32 v25, 1.0, v25
	v_min_f32_e32 v24, 0x7149f2ca, v24
	v_add_f32_e32 v26, 1.0, v26
	v_min_f32_e32 v25, 0x7149f2ca, v25
	v_add_f32_e32 v28, 1.0, v32
	v_add_f32_e32 v30, 1.0, v30
	v_add_f32_e32 v29, 1.0, v29
	v_add_f32_e32 v31, 1.0, v31
	v_rcp_f32_e32 v24, v24
	v_min_f32_e32 v26, 0x7149f2ca, v26
	v_rcp_f32_e32 v25, v25
	v_min_f32_e32 v28, 0x7149f2ca, v28
	v_min_f32_e32 v30, 0x7149f2ca, v30
	v_min_f32_e32 v29, 0x7149f2ca, v29
	v_min_f32_e32 v31, 0x7149f2ca, v31
	v_rcp_f32_e32 v26, v26
	v_rcp_f32_e32 v28, v28
	v_rcp_f32_e32 v30, v30
	v_rcp_f32_e32 v29, v29
	v_rcp_f32_e32 v31, v31
	v_pk_mul_f32 v[20:21], v[20:21], v[24:25]
	v_pk_mul_f32 v[24:25], v[16:17], v[26:27]
	v_pk_mul_f32 v[22:23], v[22:23], v[28:29]
	v_pk_mul_f32 v[26:27], v[18:19], v[30:31]
	v_cvt_pk_bf16_f32 v16, v20, v21
	v_and_b32_e32 v20, 0xffff0000, v46
	v_cvt_pk_bf16_f32 v17, v22, v23
	v_cvt_pk_bf16_f32 v18, v24, v25
	v_cvt_pk_bf16_f32 v19, v26, v27
	v_mul_f32_e32 v20, 0xbfb8aa3b, v20
	buffer_store_dwordx4 v[16:19], v52, s[8:11], 0 offen offset:256 sc1
	v_exp_f32_e32 v20, v20
	v_and_b32_e32 v21, 0xffff0000, v45
	v_lshlrev_b32_e32 v16, 16, v44
	v_and_b32_e32 v17, 0xffff0000, v44
	v_lshlrev_b32_e32 v18, 16, v46
	v_mul_f32_e32 v16, 0xbfb8aa3b, v16
	v_mul_f32_e32 v17, 0xbfb8aa3b, v17
	v_exp_f32_e32 v16, v16
	v_mul_f32_e32 v18, 0xbfb8aa3b, v18
	v_exp_f32_e32 v17, v17
	v_exp_f32_e32 v18, v18
	v_lshlrev_b32_e32 v19, 16, v45
	v_add_f32_e32 v20, 1.0, v20
	v_lshlrev_b32_e32 v22, 16, v47
	v_and_b32_e32 v23, 0xffff0000, v47
	v_min_f32_e32 v20, 0x7149f2ca, v20
	v_mul_f32_e32 v19, 0xbfb8aa3b, v19
	v_add_f32_e32 v16, 1.0, v16
	v_add_f32_e32 v17, 1.0, v17
	v_exp_f32_e32 v25, v19
	v_rcp_f32_e32 v19, v20
	v_mul_f32_e32 v20, 0xbfb8aa3b, v22
	v_mul_f32_e32 v21, 0xbfb8aa3b, v21
	v_mul_f32_e32 v23, 0xbfb8aa3b, v23
	v_min_f32_e32 v16, 0x7149f2ca, v16
	v_add_f32_e32 v18, 1.0, v18
	v_min_f32_e32 v17, 0x7149f2ca, v17
	v_exp_f32_e32 v22, v20
	v_exp_f32_e32 v21, v21
	v_exp_f32_e32 v23, v23
	v_rcp_f32_e32 v16, v16
	v_min_f32_e32 v18, 0x7149f2ca, v18
	v_rcp_f32_e32 v17, v17
	v_rcp_f32_e32 v18, v18
	v_add_f32_e32 v20, 1.0, v25
	v_add_f32_e32 v22, 1.0, v22
	v_add_f32_e32 v21, 1.0, v21
	v_add_f32_e32 v23, 1.0, v23
	v_min_f32_e32 v20, 0x7149f2ca, v20
	v_min_f32_e32 v22, 0x7149f2ca, v22
	v_min_f32_e32 v21, 0x7149f2ca, v21
	v_min_f32_e32 v23, 0x7149f2ca, v23
	v_pk_mul_f32 v[12:13], v[12:13], v[16:17]
	v_rcp_f32_e32 v20, v20
	v_rcp_f32_e32 v22, v22
	v_rcp_f32_e32 v21, v21
	v_rcp_f32_e32 v23, v23
	v_pk_mul_f32 v[16:17], v[8:9], v[18:19]
	v_cvt_pk_bf16_f32 v8, v12, v13
	v_and_b32_e32 v12, 0xffff0000, v42
	v_mul_f32_e32 v12, 0xbfb8aa3b, v12
	v_exp_f32_e32 v12, v12
	v_pk_mul_f32 v[14:15], v[14:15], v[20:21]
	v_pk_mul_f32 v[18:19], v[10:11], v[22:23]
	v_add_u32_e32 v24, 0x58000, v181
	v_cvt_pk_bf16_f32 v9, v14, v15
	v_cvt_pk_bf16_f32 v10, v16, v17
	v_cvt_pk_bf16_f32 v11, v18, v19
	buffer_store_dwordx4 v[8:11], v24, s[8:11], 0 offen sc1
	v_add_f32_e32 v12, 1.0, v12
	v_and_b32_e32 v13, 0xffff0000, v41
	v_lshlrev_b32_e32 v11, 16, v41
	v_lshlrev_b32_e32 v8, 16, v40
	v_and_b32_e32 v9, 0xffff0000, v40
	v_lshlrev_b32_e32 v10, 16, v42
	v_lshlrev_b32_e32 v14, 16, v43
	v_and_b32_e32 v15, 0xffff0000, v43
	v_min_f32_e32 v12, 0x7149f2ca, v12
	v_mul_f32_e32 v11, 0xbfb8aa3b, v11
	v_mul_f32_e32 v8, 0xbfb8aa3b, v8
	v_mul_f32_e32 v10, 0xbfb8aa3b, v10
	v_mul_f32_e32 v9, 0xbfb8aa3b, v9
	v_exp_f32_e32 v16, v11
	v_rcp_f32_e32 v11, v12
	v_mul_f32_e32 v12, 0xbfb8aa3b, v14
	v_mul_f32_e32 v13, 0xbfb8aa3b, v13
	v_mul_f32_e32 v15, 0xbfb8aa3b, v15
	v_exp_f32_e32 v8, v8
	v_exp_f32_e32 v10, v10
	v_exp_f32_e32 v9, v9
	v_exp_f32_e32 v14, v12
	v_exp_f32_e32 v13, v13
	v_exp_f32_e32 v15, v15
	v_add_f32_e32 v8, 1.0, v8
	v_add_f32_e32 v10, 1.0, v10
	v_add_f32_e32 v9, 1.0, v9
	v_add_f32_e32 v12, 1.0, v16
	v_add_f32_e32 v14, 1.0, v14
	v_add_f32_e32 v13, 1.0, v13
	v_add_f32_e32 v15, 1.0, v15
	v_min_f32_e32 v8, 0x7149f2ca, v8
	v_min_f32_e32 v10, 0x7149f2ca, v10
	v_min_f32_e32 v9, 0x7149f2ca, v9
	v_min_f32_e32 v12, 0x7149f2ca, v12
	v_min_f32_e32 v14, 0x7149f2ca, v14
	v_min_f32_e32 v13, 0x7149f2ca, v13
	v_min_f32_e32 v15, 0x7149f2ca, v15
	v_rcp_f32_e32 v8, v8
	v_rcp_f32_e32 v10, v10
	v_rcp_f32_e32 v9, v9
	v_rcp_f32_e32 v12, v12
	v_rcp_f32_e32 v14, v14
	v_rcp_f32_e32 v13, v13
	v_rcp_f32_e32 v15, v15
	v_pk_mul_f32 v[4:5], v[4:5], v[8:9]
	v_pk_mul_f32 v[8:9], v[0:1], v[10:11]
	v_pk_mul_f32 v[6:7], v[6:7], v[12:13]
	v_pk_mul_f32 v[10:11], v[2:3], v[14:15]
	v_cvt_pk_bf16_f32 v0, v4, v5
	v_cvt_pk_bf16_f32 v1, v6, v7
	v_cvt_pk_bf16_f32 v2, v8, v9
	v_cvt_pk_bf16_f32 v3, v10, v11
	buffer_store_dwordx4 v[0:3], v24, s[8:11], 0 offen offset:256 sc1
	s_waitcnt vmcnt(0)
	s_barrier

.LBB0_748:
	s_add_u32 s64, s78, 0xe700000
	s_addc_u32 s0, s79, 0
	s_lshl_b32 s2, s16, 8
	s_add_i32 s2, s2, s22
	s_lshl_b32 s1, s15, 5
	v_or_b32_e32 v176, s2, v228
	s_lshl_b32 s2, s14, 8
	s_or_b32 s1, s2, s1
	v_or_b32_e32 v200, s1, v168
	v_mov_b32_e32 v199, 0
	v_lshlrev_b32_e32 v198, 1, v200
	v_lshl_add_u64 v[104:105], s[78:79], 0, v[198:199]
	s_mov_b64 s[2:3], 0x6600000
	v_mov_b32_e32 v198, v176
	v_lshl_add_u64 v[218:219], v[104:105], 0, s[2:3]
	v_lshlrev_b64 v[202:203], 11, v[198:199]
	v_lshl_add_u64 v[116:117], v[218:219], 0, v[202:203]
	s_waitcnt vmcnt(0)
	s_barrier
	global_load_dwordx4 v[104:107], v[116:117], off nt
	global_load_dwordx4 v[222:225], v[116:117], off offset:256 nt
	v_mul_f32_e32 v92, 0xbfb8aa3b, v92
	v_mul_f32_e32 v93, 0xbfb8aa3b, v93
	v_mul_f32_e32 v94, 0xbfb8aa3b, v94
	v_mul_f32_e32 v95, 0xbfb8aa3b, v95
	v_mul_f32_e32 v80, 0xbfb8aa3b, v80
	v_mul_f32_e32 v81, 0xbfb8aa3b, v81
	v_mul_f32_e32 v82, 0xbfb8aa3b, v82
	v_mul_f32_e32 v83, 0xbfb8aa3b, v83
	v_exp_f32_e32 v92, v92
	v_exp_f32_e32 v93, v93
	v_exp_f32_e32 v94, v94
	v_exp_f32_e32 v95, v95
	v_exp_f32_e32 v80, v80
	v_exp_f32_e32 v81, v81
	v_exp_f32_e32 v82, v82
	v_exp_f32_e32 v83, v83
	v_add_f32_e32 v92, 1.0, v92
	v_add_f32_e32 v93, 1.0, v93
	v_add_f32_e32 v94, 1.0, v94
	v_add_f32_e32 v95, 1.0, v95
	v_mov_b32_e32 v197, v199
	v_or_b32_e32 v196, 16, v176
	v_add_f32_e32 v116, 1.0, v80
	v_add_f32_e32 v117, 1.0, v81
	v_add_f32_e32 v118, 1.0, v82
	v_add_f32_e32 v119, 1.0, v83
	v_rcp_f32_e32 v80, v92
	v_rcp_f32_e32 v81, v93
	v_rcp_f32_e32 v82, v94
	v_rcp_f32_e32 v83, v95
	v_mov_b32_e32 v193, v199
	v_mov_b32_e32 v185, v199
	v_or_b32_e32 v192, 32, v176
	v_or_b32_e32 v184, 48, v176
	v_lshlrev_b64 v[216:217], 11, v[196:197]
	v_lshlrev_b64 v[208:209], 11, v[192:193]
	v_lshlrev_b64 v[204:205], 11, v[184:185]
	v_rcp_f32_e32 v92, v116
	v_rcp_f32_e32 v93, v117
	v_lshl_add_u64 v[116:117], v[218:219], 0, v[216:217]
	v_rcp_f32_e32 v94, v118
	v_rcp_f32_e32 v95, v119
	v_lshl_add_u64 v[118:119], v[218:219], 0, v[208:209]
	v_lshl_add_u64 v[124:125], v[218:219], 0, v[204:205]
	global_load_dwordx4 v[172:175], v[116:117], off nt
	global_load_dwordx4 v[168:171], v[116:117], off offset:256 nt
	global_load_dwordx4 v[164:167], v[118:119], off nt
	global_load_dwordx4 v[160:163], v[118:119], off offset:256 nt
	global_load_dwordx4 v[156:159], v[124:125], off nt
	global_load_dwordx4 v[152:155], v[124:125], off offset:256 nt
	v_add_u32_e32 v182, 0x80, v176
	v_mov_b32_e32 v183, v199
	v_lshlrev_b64 v[194:195], 11, v[182:183]
	v_add_u32_e32 v180, 0x90, v176
	v_mov_b32_e32 v181, v199
	v_lshlrev_b64 v[190:191], 11, v[180:181]
	v_add_u32_e32 v178, 0xa0, v176
	v_mov_b32_e32 v179, v199
	v_lshlrev_b64 v[186:187], 11, v[178:179]
	v_add_u32_e32 v176, 0xb0, v176
	v_mov_b32_e32 v177, v199
	v_lshlrev_b64 v[188:189], 11, v[176:177]
	v_mul_f32_e32 v140, 0xbfb8aa3b, v140
	v_exp_f32_e32 v140, v140
	v_mul_f32_e32 v132, 0xbfb8aa3b, v132
	v_exp_f32_e32 v132, v132
	s_and_b32 s65, s0, 0xffff
	s_mov_b32 s67, 0x20000
	s_mov_b32 s66, 0x100000
	v_add_f32_e32 v132, 1.0, v132
	v_cmp_eq_u32_e64 s[0:1], 0, v201
	s_waitcnt vmcnt(0)
	v_lshlrev_b32_e32 v116, 16, v104
	v_and_b32_e32 v117, 0xffff0000, v104
	v_lshlrev_b32_e32 v104, 16, v105
	v_and_b32_e32 v105, 0xffff0000, v105
	v_pk_mul_f32 v[212:213], v[82:83], v[104:105]
	v_pk_mul_f32 v[214:215], v[80:81], v[116:117]
	v_mul_f32_e32 v81, v213, v213
	v_mul_f32_e32 v80, v215, v215
	v_fmac_f32_e32 v80, v214, v214
	v_fmac_f32_e32 v81, v212, v212
	v_add_f32_e32 v227, v80, v81
	v_lshl_add_u64 v[80:81], v[218:219], 0, v[194:195]
	global_load_dwordx4 v[148:151], v[80:81], off nt
	global_load_dwordx4 v[144:147], v[80:81], off offset:256 nt
	v_lshl_add_u64 v[80:81], v[218:219], 0, v[190:191]
	v_lshlrev_b32_e32 v118, 16, v106
	v_and_b32_e32 v119, 0xffff0000, v106
	v_lshlrev_b32_e32 v106, 16, v107
	v_and_b32_e32 v107, 0xffff0000, v107
	global_load_dwordx4 v[136:139], v[80:81], off nt
	global_load_dwordx4 v[124:127], v[80:81], off offset:256 nt
	v_lshl_add_u64 v[80:81], v[218:219], 0, v[186:187]
	v_pk_mul_f32 v[206:207], v[94:95], v[106:107]
	v_pk_mul_f32 v[210:211], v[92:93], v[118:119]
	global_load_dwordx4 v[116:119], v[80:81], off nt
	global_load_dwordx4 v[104:107], v[80:81], off offset:256 nt
	v_lshl_add_u64 v[80:81], v[218:219], 0, v[188:189]
	global_load_dwordx4 v[92:95], v[80:81], off nt
	s_nop 0
	global_load_dwordx4 v[80:83], v[80:81], off offset:256 nt
	v_mul_f32_e32 v221, v211, v211
	v_mul_f32_e32 v226, v207, v207
	v_fmac_f32_e32 v221, v210, v210
	v_fmac_f32_e32 v226, v206, v206
	v_add_f32_e32 v218, v221, v226
	v_add_f32_e32 v226, 1.0, v140
	v_mul_f32_e32 v140, 0xbfb8aa3b, v141
	v_mul_f32_e32 v141, 0xbfb8aa3b, v142
	v_mul_f32_e32 v142, 0xbfb8aa3b, v143
	v_exp_f32_e32 v141, v141
	v_exp_f32_e32 v142, v142
	v_exp_f32_e32 v143, v140
	v_add_f32_e32 v221, v227, v218
	v_add_f32_e32 v140, 1.0, v141
	v_add_f32_e32 v141, 1.0, v142
	v_rcp_f32_e32 v140, v140
	v_rcp_f32_e32 v141, v141
	v_lshlrev_b32_e32 v218, 16, v222
	v_and_b32_e32 v219, 0xffff0000, v222
	v_lshlrev_b32_e32 v222, 16, v223
	v_and_b32_e32 v223, 0xffff0000, v223
	v_pk_mul_f32 v[140:141], v[140:141], v[222:223]
	v_rcp_f32_e32 v222, v132
	v_mul_f32_e32 v132, 0xbfb8aa3b, v133
	v_mul_f32_e32 v133, 0xbfb8aa3b, v134
	v_mul_f32_e32 v134, 0xbfb8aa3b, v135
	v_exp_f32_e32 v132, v132
	v_exp_f32_e32 v133, v133
	v_exp_f32_e32 v134, v134
	v_add_f32_e32 v143, 1.0, v143
	v_rcp_f32_e32 v142, v226
	v_rcp_f32_e32 v143, v143
	v_add_f32_e32 v135, 1.0, v132
	v_add_f32_e32 v132, 1.0, v133
	v_add_f32_e32 v133, 1.0, v134
	v_rcp_f32_e32 v132, v132
	v_rcp_f32_e32 v133, v133
	v_rcp_f32_e32 v223, v135
	v_pk_mul_f32 v[142:143], v[142:143], v[218:219]
	v_lshlrev_b32_e32 v218, 16, v224
	v_and_b32_e32 v219, 0xffff0000, v224
	v_lshlrev_b32_e32 v134, 16, v225
	v_and_b32_e32 v135, 0xffff0000, v225
	v_pk_mul_f32 v[132:133], v[132:133], v[134:135]
	v_pk_mul_f32 v[134:135], v[222:223], v[218:219]
	v_mul_f32_e32 v218, v143, v143
	v_mul_f32_e32 v219, v141, v141
	v_fmac_f32_e32 v218, v142, v142
	v_fmac_f32_e32 v219, v140, v140
	v_add_f32_e32 v218, v218, v219
	v_mul_f32_e32 v219, v135, v135
	v_mul_f32_e32 v222, v133, v133
	v_fmac_f32_e32 v219, v134, v134
	v_fmac_f32_e32 v222, v132, v132
	v_add_f32_e32 v219, v219, v222
	v_add_f32_e32 v218, v218, v219
	v_add_f32_e32 v221, v221, v218
	v_mbcnt_lo_u32_b32 v218, -1, 0
	v_mbcnt_hi_u32_b32 v219, -1, v218
	v_and_b32_e32 v222, 64, v219
	v_xor_b32_e32 v218, 16, v219
	v_add_u32_e32 v222, 64, v222
	v_cmp_lt_i32_e32 vcc, v218, v222
	v_xor_b32_e32 v224, 32, v219
	s_nop 0
	v_cndmask_b32_e32 v218, v219, v218, vcc
	v_lshlrev_b32_e32 v218, 2, v218
	ds_bpermute_b32 v223, v218, v221
	v_cmp_lt_i32_e32 vcc, v224, v222
	s_waitcnt lgkmcnt(0)
	v_add_f32_e32 v221, v221, v223
	v_cndmask_b32_e32 v219, v219, v224, vcc
	v_lshlrev_b32_e32 v219, 2, v219
	ds_bpermute_b32 v222, v219, v221
	v_cmp_ne_u32_e32 vcc, 0, v201
	s_and_saveexec_b64 s[2:3], s[0:1]
	s_cbranch_execz .LBB0_750
	s_lshl_b32 s4, s14, 4
	s_lshl_b32 s5, s15, 2
	s_or_b32 s4, s4, s5
	s_waitcnt lgkmcnt(0)
	v_add_f32_e32 v201, v221, v222
	v_lshl_add_u32 v221, v198, 6, s4
	buffer_store_dword v201, v221, s[64:67], 0 offen sc1
